# v20: v15 + GEMM K-loops without the per-MFMA-block s_setprio toggles; one static s_setprio 1 for the leading half-workgroup (waves 0-3) at each GEMM phase entry, reset at exit
# baseline (speedup 1.0000x reference)
.LBB0_84:
	s_cmp_lt_i32 s66, 2
	s_cselect_b64 s[2:3], -1, 0
	s_add_u32 s70, s86, 0x7000000
	s_addc_u32 s71, s87, 0
	s_add_u32 s94, s86, 0xf000000
	s_addc_u32 s95, s87, 0
	s_and_b64 s[6:7], s[2:3], s[4:5]
	s_mov_b32 s74, s52
	s_andn2_b64 vcc, exec, s[6:7]
	s_cbranch_vccnz .LBB0_105
	s_cmpk_gt_i32 s64, 0x7ff
	v_readfirstlane_b32 s2, v0
	s_cbranch_scc1 .LBB0_105
	s_cmpk_lt_u32 s2, 0x100
	s_cbranch_scc0 .Lsp_g1
	s_setprio 1
.Lsp_g1:
	s_ashr_i32 s3, s64, 31
	s_lshr_b32 s4, s3, 29
	s_add_i32 s8, s64, s4
	s_and_b32 s4, s8, -8
	s_sub_i32 s10, s64, s4
	s_cmp_gt_i32 s10, -1
	s_cbranch_scc0 .LBB0_88
	s_lshl_b32 s9, s10, 8
	s_cbranch_execz .LBB0_89
	s_branch .LBB0_90

.LBB0_100:
	ds_read_b128 v[154:157], v150
	ds_read_b128 v[158:161], v150 offset:1024
	ds_read_b128 v[162:165], v150 offset:2048
	ds_read_b128 v[166:169], v150 offset:3072
	ds_read_b128 v[172:175], v151
	ds_read_b128 v[176:179], v151 offset:1024
	ds_read_b128 v[180:183], v151 offset:2048
	ds_read_b128 v[184:187], v151 offset:3072
	s_add_u32 s30, s28, 0xfff80080
	s_addc_u32 s31, s29, -1
	s_cmp_eq_u32 s50, 28
	s_cselect_b32 s35, s19, s31
	s_cselect_b32 s34, s46, s30
	s_cselect_b32 s31, s17, s49
	s_cselect_b32 s30, s47, s48
	v_lshl_add_u64 v[146:147], s[28:29], 0, v[138:139]
	s_add_i32 m0, s27, 0xc000
	ds_read_b128 v[188:191], v152
	ds_read_b128 v[192:195], v152 offset:1024
	ds_read_b128 v[196:199], v152 offset:2048
	ds_read_b128 v[200:203], v152 offset:3072
	ds_read_b128 v[204:207], v152 offset:4096
	ds_read_b128 v[208:211], v152 offset:5120
	ds_read_b128 v[212:215], v152 offset:6144
	ds_read_b128 v[216:219], v152 offset:7168
	global_load_lds_dwordx4 v[146:147], off
	v_lshl_add_u64 v[146:147], s[28:29], 0, v[140:141]
	s_add_i32 m0, s27, 0xe000
	s_nop 0
	global_load_lds_dwordx4 v[146:147], off
	s_waitcnt vmcnt(8)
	s_waitcnt lgkmcnt(0)
	s_barrier
	s_waitcnt lgkmcnt(0)
	v_mfma_f32_16x16x32_bf16 v[126:129], v[154:157], v[188:191], v[126:129]
	v_mfma_f32_16x16x32_bf16 v[122:125], v[162:165], v[188:191], v[122:125]
	v_mfma_f32_16x16x32_bf16 v[118:121], v[154:157], v[196:199], v[118:121]
	v_mfma_f32_16x16x32_bf16 v[110:113], v[162:165], v[196:199], v[110:113]
	v_mfma_f32_16x16x32_bf16 v[102:105], v[154:157], v[204:207], v[102:105]
	v_mfma_f32_16x16x32_bf16 v[94:97], v[162:165], v[204:207], v[94:97]
	v_mfma_f32_16x16x32_bf16 v[86:89], v[154:157], v[212:215], v[86:89]
	v_mfma_f32_16x16x32_bf16 v[78:81], v[162:165], v[212:215], v[78:81]
	v_mfma_f32_16x16x32_bf16 v[126:129], v[158:161], v[192:195], v[126:129]
	v_mfma_f32_16x16x32_bf16 v[122:125], v[166:169], v[192:195], v[122:125]
	v_mfma_f32_16x16x32_bf16 v[118:121], v[158:161], v[200:203], v[118:121]
	v_mfma_f32_16x16x32_bf16 v[110:113], v[166:169], v[200:203], v[110:113]
	v_mfma_f32_16x16x32_bf16 v[102:105], v[158:161], v[208:211], v[102:105]
	v_mfma_f32_16x16x32_bf16 v[94:97], v[166:169], v[208:211], v[94:97]
	v_mfma_f32_16x16x32_bf16 v[86:89], v[158:161], v[216:219], v[86:89]
	v_mfma_f32_16x16x32_bf16 v[78:81], v[166:169], v[216:219], v[78:81]
	v_mfma_f32_16x16x32_bf16 v[114:117], v[172:175], v[188:191], v[114:117]
	v_mfma_f32_16x16x32_bf16 v[106:109], v[180:183], v[188:191], v[106:109]
	v_mfma_f32_16x16x32_bf16 v[98:101], v[172:175], v[196:199], v[98:101]
	v_mfma_f32_16x16x32_bf16 v[90:93], v[180:183], v[196:199], v[90:93]
	v_mfma_f32_16x16x32_bf16 v[82:85], v[172:175], v[204:207], v[82:85]
	v_mfma_f32_16x16x32_bf16 v[74:77], v[180:183], v[204:207], v[74:77]
	v_mfma_f32_16x16x32_bf16 v[70:73], v[172:175], v[212:215], v[70:73]
	v_mfma_f32_16x16x32_bf16 v[66:69], v[180:183], v[212:215], v[66:69]
	v_mfma_f32_16x16x32_bf16 v[114:117], v[176:179], v[192:195], v[114:117]
	v_mfma_f32_16x16x32_bf16 v[106:109], v[184:187], v[192:195], v[106:109]
	v_mfma_f32_16x16x32_bf16 v[98:101], v[176:179], v[200:203], v[98:101]
	v_mfma_f32_16x16x32_bf16 v[90:93], v[184:187], v[200:203], v[90:93]
	v_mfma_f32_16x16x32_bf16 v[82:85], v[176:179], v[208:211], v[82:85]
	v_mfma_f32_16x16x32_bf16 v[74:77], v[184:187], v[208:211], v[74:77]
	v_mfma_f32_16x16x32_bf16 v[70:73], v[176:179], v[216:219], v[70:73]
	v_mfma_f32_16x16x32_bf16 v[66:69], v[184:187], v[216:219], v[66:69]
	s_barrier
	s_add_i32 s51, s43, s33
	v_lshl_add_u64 v[146:147], s[30:31], 0, v[132:133]
	s_mov_b32 m0, s51
	ds_read_b128 v[188:191], v152 offset:16384
	ds_read_b128 v[192:195], v152 offset:17408
	ds_read_b128 v[196:199], v152 offset:18432
	ds_read_b128 v[200:203], v152 offset:19456
	ds_read_b128 v[204:207], v152 offset:20480
	ds_read_b128 v[208:211], v152 offset:21504
	ds_read_b128 v[212:215], v152 offset:22528
	ds_read_b128 v[216:219], v152 offset:23552
	global_load_lds_dwordx4 v[146:147], off
	s_add_i32 m0, s51, 0x2000
	s_add_u32 s52, s30, 0x80000
	v_lshl_add_u64 v[220:221], s[30:31], 0, v[136:137]
	s_addc_u32 s53, s31, 0
	s_add_i32 s51, s44, s33
	global_load_lds_dwordx4 v[220:221], off
	v_lshl_add_u64 v[222:223], s[52:53], 0, v[132:133]
	s_mov_b32 m0, s51
	v_lshl_add_u64 v[224:225], s[34:35], 0, v[134:135]
	global_load_lds_dwordx4 v[222:223], off
	v_lshl_add_u64 v[222:223], s[52:53], 0, v[136:137]
	s_add_i32 m0, s51, 0x2000
	s_nop 0
	global_load_lds_dwordx4 v[222:223], off
	v_lshl_add_u64 v[222:223], s[34:35], 0, v[130:131]
	s_mov_b32 m0, s27
	s_nop 0
	global_load_lds_dwordx4 v[222:223], off
	s_mov_b32 m0, s36
	s_nop 0
	global_load_lds_dwordx4 v[224:225], off
	s_waitcnt vmcnt(8)
	s_waitcnt lgkmcnt(0)
	s_barrier
	s_waitcnt lgkmcnt(0)
	v_mfma_f32_16x16x32_bf16 v[62:65], v[154:157], v[188:191], v[62:65]
	v_mfma_f32_16x16x32_bf16 v[58:61], v[162:165], v[188:191], v[58:61]
	v_mfma_f32_16x16x32_bf16 v[54:57], v[154:157], v[196:199], v[54:57]
	v_mfma_f32_16x16x32_bf16 v[46:49], v[162:165], v[196:199], v[46:49]
	v_mfma_f32_16x16x32_bf16 v[38:41], v[154:157], v[204:207], v[38:41]
	v_mfma_f32_16x16x32_bf16 v[30:33], v[162:165], v[204:207], v[30:33]
	v_mfma_f32_16x16x32_bf16 v[22:25], v[154:157], v[212:215], v[22:25]
	v_mfma_f32_16x16x32_bf16 v[14:17], v[162:165], v[212:215], v[14:17]
	v_mfma_f32_16x16x32_bf16 v[62:65], v[158:161], v[192:195], v[62:65]
	v_mfma_f32_16x16x32_bf16 v[58:61], v[166:169], v[192:195], v[58:61]
	v_mfma_f32_16x16x32_bf16 v[54:57], v[158:161], v[200:203], v[54:57]
	v_mfma_f32_16x16x32_bf16 v[46:49], v[166:169], v[200:203], v[46:49]
	v_mfma_f32_16x16x32_bf16 v[38:41], v[158:161], v[208:211], v[38:41]
	v_mfma_f32_16x16x32_bf16 v[30:33], v[166:169], v[208:211], v[30:33]
	v_mfma_f32_16x16x32_bf16 v[22:25], v[158:161], v[216:219], v[22:25]
	v_mfma_f32_16x16x32_bf16 v[14:17], v[166:169], v[216:219], v[14:17]
	v_mfma_f32_16x16x32_bf16 v[50:53], v[172:175], v[188:191], v[50:53]
	v_mfma_f32_16x16x32_bf16 v[42:45], v[180:183], v[188:191], v[42:45]
	v_mfma_f32_16x16x32_bf16 v[34:37], v[172:175], v[196:199], v[34:37]
	v_mfma_f32_16x16x32_bf16 v[26:29], v[180:183], v[196:199], v[26:29]
	v_mfma_f32_16x16x32_bf16 v[18:21], v[172:175], v[204:207], v[18:21]
	v_mfma_f32_16x16x32_bf16 v[10:13], v[180:183], v[204:207], v[10:13]
	v_mfma_f32_16x16x32_bf16 v[6:9], v[172:175], v[212:215], v[6:9]
	v_mfma_f32_16x16x32_bf16 v[2:5], v[180:183], v[212:215], v[2:5]
	v_mfma_f32_16x16x32_bf16 v[50:53], v[176:179], v[192:195], v[50:53]
	v_mfma_f32_16x16x32_bf16 v[42:45], v[184:187], v[192:195], v[42:45]
	v_mfma_f32_16x16x32_bf16 v[34:37], v[176:179], v[200:203], v[34:37]
	v_mfma_f32_16x16x32_bf16 v[26:29], v[184:187], v[200:203], v[26:29]
	v_mfma_f32_16x16x32_bf16 v[18:21], v[176:179], v[208:211], v[18:21]
	v_mfma_f32_16x16x32_bf16 v[10:13], v[184:187], v[208:211], v[10:13]
	v_mfma_f32_16x16x32_bf16 v[6:9], v[176:179], v[216:219], v[6:9]
	v_mfma_f32_16x16x32_bf16 v[2:5], v[184:187], v[216:219], v[2:5]
	s_barrier
	s_add_i32 s51, 0, 0x18000
	v_add_u32_e32 v153, s51, v148
	s_add_i32 s52, 0, 0x1c000
	ds_read_b128 v[154:157], v153
	ds_read_b128 v[158:161], v153 offset:1024
	ds_read_b128 v[162:165], v153 offset:2048
	ds_read_b128 v[166:169], v153 offset:3072
	v_add_u32_e32 v153, s52, v148
	ds_read_b128 v[172:175], v153
	ds_read_b128 v[176:179], v153 offset:1024
	ds_read_b128 v[180:183], v153 offset:2048
	ds_read_b128 v[184:187], v153 offset:3072
	s_add_u32 s34, s34, 0x80000
	s_addc_u32 s35, s35, 0
	s_mov_b32 m0, s37
	v_lshl_add_u64 v[226:227], s[34:35], 0, v[130:131]
	ds_read_b128 v[188:191], v152 offset:32768
	ds_read_b128 v[192:195], v152 offset:33792
	ds_read_b128 v[196:199], v152 offset:34816
	ds_read_b128 v[200:203], v152 offset:35840
	ds_read_b128 v[204:207], v152 offset:36864
	ds_read_b128 v[208:211], v152 offset:37888
	ds_read_b128 v[212:215], v152 offset:38912
	ds_read_b128 v[216:219], v152 offset:39936
	global_load_lds_dwordx4 v[226:227], off
	v_lshl_add_u64 v[226:227], s[34:35], 0, v[134:135]
	s_mov_b32 m0, s38
	s_nop 0
	global_load_lds_dwordx4 v[226:227], off
	s_waitcnt vmcnt(8)
	s_waitcnt lgkmcnt(0)
	s_barrier
	s_waitcnt lgkmcnt(0)
	v_mfma_f32_16x16x32_bf16 v[126:129], v[154:157], v[188:191], v[126:129]
	v_mfma_f32_16x16x32_bf16 v[122:125], v[162:165], v[188:191], v[122:125]
	v_mfma_f32_16x16x32_bf16 v[118:121], v[154:157], v[196:199], v[118:121]
	v_mfma_f32_16x16x32_bf16 v[110:113], v[162:165], v[196:199], v[110:113]
	v_mfma_f32_16x16x32_bf16 v[102:105], v[154:157], v[204:207], v[102:105]
	v_mfma_f32_16x16x32_bf16 v[94:97], v[162:165], v[204:207], v[94:97]
	v_mfma_f32_16x16x32_bf16 v[86:89], v[154:157], v[212:215], v[86:89]
	v_mfma_f32_16x16x32_bf16 v[78:81], v[162:165], v[212:215], v[78:81]
	v_mfma_f32_16x16x32_bf16 v[126:129], v[158:161], v[192:195], v[126:129]
	v_mfma_f32_16x16x32_bf16 v[122:125], v[166:169], v[192:195], v[122:125]
	v_mfma_f32_16x16x32_bf16 v[118:121], v[158:161], v[200:203], v[118:121]
	v_mfma_f32_16x16x32_bf16 v[110:113], v[166:169], v[200:203], v[110:113]
	v_mfma_f32_16x16x32_bf16 v[102:105], v[158:161], v[208:211], v[102:105]
	v_mfma_f32_16x16x32_bf16 v[94:97], v[166:169], v[208:211], v[94:97]
	v_mfma_f32_16x16x32_bf16 v[86:89], v[158:161], v[216:219], v[86:89]
	v_mfma_f32_16x16x32_bf16 v[78:81], v[166:169], v[216:219], v[78:81]
	v_mfma_f32_16x16x32_bf16 v[114:117], v[172:175], v[188:191], v[114:117]
	v_mfma_f32_16x16x32_bf16 v[106:109], v[180:183], v[188:191], v[106:109]
	v_mfma_f32_16x16x32_bf16 v[98:101], v[172:175], v[196:199], v[98:101]
	v_mfma_f32_16x16x32_bf16 v[90:93], v[180:183], v[196:199], v[90:93]
	v_mfma_f32_16x16x32_bf16 v[82:85], v[172:175], v[204:207], v[82:85]
	v_mfma_f32_16x16x32_bf16 v[74:77], v[180:183], v[204:207], v[74:77]
	v_mfma_f32_16x16x32_bf16 v[70:73], v[172:175], v[212:215], v[70:73]
	v_mfma_f32_16x16x32_bf16 v[66:69], v[180:183], v[212:215], v[66:69]
	v_mfma_f32_16x16x32_bf16 v[114:117], v[176:179], v[192:195], v[114:117]
	v_mfma_f32_16x16x32_bf16 v[106:109], v[184:187], v[192:195], v[106:109]
	v_mfma_f32_16x16x32_bf16 v[98:101], v[176:179], v[200:203], v[98:101]
	v_mfma_f32_16x16x32_bf16 v[90:93], v[184:187], v[200:203], v[90:93]
	v_mfma_f32_16x16x32_bf16 v[82:85], v[176:179], v[208:211], v[82:85]
	v_mfma_f32_16x16x32_bf16 v[74:77], v[184:187], v[208:211], v[74:77]
	v_mfma_f32_16x16x32_bf16 v[70:73], v[176:179], v[216:219], v[70:73]
	v_mfma_f32_16x16x32_bf16 v[66:69], v[184:187], v[216:219], v[66:69]
	s_barrier
	s_add_i32 s34, s51, s33
	v_lshl_add_u64 v[146:147], v[146:147], 0, s[8:9]
	s_mov_b32 m0, s34
	ds_read_b128 v[188:191], v152 offset:49152
	ds_read_b128 v[192:195], v152 offset:50176
	ds_read_b128 v[196:199], v152 offset:51200
	ds_read_b128 v[200:203], v152 offset:52224
	ds_read_b128 v[204:207], v152 offset:53248
	ds_read_b128 v[208:211], v152 offset:54272
	ds_read_b128 v[212:215], v152 offset:55296
	ds_read_b128 v[216:219], v152 offset:56320
	global_load_lds_dwordx4 v[146:147], off
	s_add_i32 m0, s34, 0x2000
	s_add_u32 s30, s30, 0x80080
	v_lshl_add_u64 v[146:147], v[220:221], 0, s[8:9]
	s_addc_u32 s31, s31, 0
	s_add_i32 s34, s52, s33
	global_load_lds_dwordx4 v[146:147], off
	v_lshl_add_u64 v[146:147], s[30:31], 0, v[132:133]
	s_mov_b32 m0, s34
	s_nop 0
	global_load_lds_dwordx4 v[146:147], off
	v_lshl_add_u64 v[146:147], s[30:31], 0, v[136:137]
	s_add_i32 m0, s34, 0x2000
	s_nop 0
	global_load_lds_dwordx4 v[146:147], off
	v_lshl_add_u64 v[146:147], v[222:223], 0, s[8:9]
	s_mov_b32 m0, s40
	s_nop 0
	global_load_lds_dwordx4 v[146:147], off
	v_lshl_add_u64 v[146:147], v[224:225], 0, s[8:9]
	s_mov_b32 m0, s41
	s_nop 0
	global_load_lds_dwordx4 v[146:147], off
	s_waitcnt vmcnt(8)
	s_waitcnt lgkmcnt(0)
	s_barrier
	s_waitcnt lgkmcnt(0)
	v_mfma_f32_16x16x32_bf16 v[62:65], v[154:157], v[188:191], v[62:65]
	v_mfma_f32_16x16x32_bf16 v[58:61], v[162:165], v[188:191], v[58:61]
	v_mfma_f32_16x16x32_bf16 v[54:57], v[154:157], v[196:199], v[54:57]
	v_mfma_f32_16x16x32_bf16 v[46:49], v[162:165], v[196:199], v[46:49]
	v_mfma_f32_16x16x32_bf16 v[38:41], v[154:157], v[204:207], v[38:41]
	v_mfma_f32_16x16x32_bf16 v[30:33], v[162:165], v[204:207], v[30:33]
	v_mfma_f32_16x16x32_bf16 v[22:25], v[154:157], v[212:215], v[22:25]
	v_mfma_f32_16x16x32_bf16 v[14:17], v[162:165], v[212:215], v[14:17]
	v_mfma_f32_16x16x32_bf16 v[62:65], v[158:161], v[192:195], v[62:65]
	v_mfma_f32_16x16x32_bf16 v[58:61], v[166:169], v[192:195], v[58:61]
	v_mfma_f32_16x16x32_bf16 v[54:57], v[158:161], v[200:203], v[54:57]
	v_mfma_f32_16x16x32_bf16 v[46:49], v[166:169], v[200:203], v[46:49]
	v_mfma_f32_16x16x32_bf16 v[38:41], v[158:161], v[208:211], v[38:41]
	v_mfma_f32_16x16x32_bf16 v[30:33], v[166:169], v[208:211], v[30:33]
	v_mfma_f32_16x16x32_bf16 v[22:25], v[158:161], v[216:219], v[22:25]
	v_mfma_f32_16x16x32_bf16 v[14:17], v[166:169], v[216:219], v[14:17]
	v_mfma_f32_16x16x32_bf16 v[50:53], v[172:175], v[188:191], v[50:53]
	v_mfma_f32_16x16x32_bf16 v[42:45], v[180:183], v[188:191], v[42:45]
	v_mfma_f32_16x16x32_bf16 v[34:37], v[172:175], v[196:199], v[34:37]
	v_mfma_f32_16x16x32_bf16 v[26:29], v[180:183], v[196:199], v[26:29]
	v_mfma_f32_16x16x32_bf16 v[18:21], v[172:175], v[204:207], v[18:21]
	v_mfma_f32_16x16x32_bf16 v[10:13], v[180:183], v[204:207], v[10:13]
	v_mfma_f32_16x16x32_bf16 v[6:9], v[172:175], v[212:215], v[6:9]
	v_mfma_f32_16x16x32_bf16 v[2:5], v[180:183], v[212:215], v[2:5]
	v_mfma_f32_16x16x32_bf16 v[50:53], v[176:179], v[192:195], v[50:53]
	v_mfma_f32_16x16x32_bf16 v[42:45], v[184:187], v[192:195], v[42:45]
	v_mfma_f32_16x16x32_bf16 v[34:37], v[176:179], v[200:203], v[34:37]
	v_mfma_f32_16x16x32_bf16 v[26:29], v[184:187], v[200:203], v[26:29]
	v_mfma_f32_16x16x32_bf16 v[18:21], v[176:179], v[208:211], v[18:21]
	v_mfma_f32_16x16x32_bf16 v[10:13], v[184:187], v[208:211], v[10:13]
	v_mfma_f32_16x16x32_bf16 v[6:9], v[176:179], v[216:219], v[6:9]
	v_mfma_f32_16x16x32_bf16 v[2:5], v[184:187], v[216:219], v[2:5]
	s_barrier
	s_add_i32 s50, s50, 2
	s_add_u32 s28, s28, 0x100
	s_addc_u32 s29, s29, 0
	s_add_u32 s48, s48, 0x100
	s_addc_u32 s49, s49, 0
	s_cmp_gt_u32 s50, 29
	s_cbranch_scc0 .LBB0_100
	s_ashr_i32 s17, s45, 31
	s_lshr_b32 s17, s17, 30
	s_add_i32 s17, s45, s17
	s_ashr_i32 s28, s17, 2
	s_ashr_i32 s29, s28, 31
	s_lshl_b64 s[30:31], s[28:29], 25
	s_add_u32 s30, s94, s30
	s_addc_u32 s31, s95, s31
	v_lshl_or_b32 v146, s45, 8, v149
	s_lshl_b32 s17, s28, 10
	v_lshl_add_u32 v154, s26, 8, v1
	v_subrev_u32_e32 v146, s17, v146
	v_ashrrev_i32_e32 v147, 31, v146
	v_ashrrev_i32_e32 v155, 31, v154
	v_lshl_add_u64 v[156:157], v[146:147], 1, s[30:31]
	v_lshlrev_b64 v[146:147], 11, v[154:155]
	v_lshl_add_u64 v[146:147], v[156:157], 0, v[146:147]
	v_cvt_pk_bf16_f32 v126, v126, v127
	v_cvt_pk_bf16_f32 v127, v128, v129
	v_cvt_pk_bf16_f32 v128, v122, v123
	v_cvt_pk_bf16_f32 v129, v124, v125
	s_mov_b64 s[28:29], 0x40000
	global_store_dwordx4 v[146:147], v[126:129], off sc1
	s_nop 1
	v_cvt_pk_bf16_f32 v114, v114, v115
	v_cvt_pk_bf16_f32 v115, v116, v117
	v_cvt_pk_bf16_f32 v116, v106, v107
	v_lshl_add_u64 v[106:107], v[146:147], 0, s[10:11]
	v_cvt_pk_bf16_f32 v117, v108, v109
	s_and_b64 vcc, exec, s[4:5]
	global_store_dwordx4 v[106:107], v[114:117], off sc1
	s_nop 1
	v_or_b32_e32 v106, 16, v154
	v_ashrrev_i32_e32 v107, 31, v106
	v_lshlrev_b64 v[106:107], 11, v[106:107]
	v_lshl_add_u64 v[114:115], v[156:157], 0, v[106:107]
	v_cvt_pk_bf16_f32 v106, v118, v119
	v_cvt_pk_bf16_f32 v107, v120, v121
	v_cvt_pk_bf16_f32 v108, v110, v111
	v_cvt_pk_bf16_f32 v109, v112, v113
	s_mov_b32 s45, s16
	global_store_dwordx4 v[114:115], v[106:109], off sc1
	s_nop 1
	v_cvt_pk_bf16_f32 v98, v98, v99
	v_cvt_pk_bf16_f32 v99, v100, v101
	v_cvt_pk_bf16_f32 v100, v90, v91
	v_lshl_add_u64 v[90:91], v[114:115], 0, s[10:11]
	v_cvt_pk_bf16_f32 v101, v92, v93
	s_mov_b32 s26, s18
	global_store_dwordx4 v[90:91], v[98:101], off sc1
	s_nop 1
	v_or_b32_e32 v90, 32, v154
	v_ashrrev_i32_e32 v91, 31, v90
	v_lshlrev_b64 v[90:91], 11, v[90:91]
	v_lshl_add_u64 v[98:99], v[156:157], 0, v[90:91]
	v_cvt_pk_bf16_f32 v90, v102, v103
	v_cvt_pk_bf16_f32 v91, v104, v105
	v_cvt_pk_bf16_f32 v92, v94, v95
	v_cvt_pk_bf16_f32 v93, v96, v97
	s_mov_b64 s[30:31], s[24:25]
	global_store_dwordx4 v[98:99], v[90:93], off sc1
	s_nop 1
	v_cvt_pk_bf16_f32 v82, v82, v83
	v_cvt_pk_bf16_f32 v83, v84, v85
	v_cvt_pk_bf16_f32 v84, v74, v75
	v_lshl_add_u64 v[74:75], v[98:99], 0, s[10:11]
	v_cvt_pk_bf16_f32 v85, v76, v77
	s_nop 0
	global_store_dwordx4 v[74:75], v[82:85], off sc1
	s_nop 1
	v_or_b32_e32 v74, 48, v154
	v_ashrrev_i32_e32 v75, 31, v74
	v_lshlrev_b64 v[74:75], 11, v[74:75]
	v_lshl_add_u64 v[82:83], v[156:157], 0, v[74:75]
	v_cvt_pk_bf16_f32 v74, v86, v87
	v_cvt_pk_bf16_f32 v75, v88, v89
	v_cvt_pk_bf16_f32 v76, v78, v79
	v_cvt_pk_bf16_f32 v77, v80, v81
	s_nop 0
	global_store_dwordx4 v[82:83], v[74:77], off sc1
	s_nop 1
	v_cvt_pk_bf16_f32 v70, v70, v71
	v_cvt_pk_bf16_f32 v71, v72, v73
	v_cvt_pk_bf16_f32 v72, v66, v67
	v_lshl_add_u64 v[66:67], v[82:83], 0, s[10:11]
	v_cvt_pk_bf16_f32 v73, v68, v69
	s_nop 0
	global_store_dwordx4 v[66:67], v[70:73], off sc1
	s_nop 1
	v_lshl_add_u64 v[66:67], v[146:147], 0, s[28:29]
	s_mov_b64 s[28:29], 0x40100
	v_cvt_pk_bf16_f32 v62, v62, v63
	v_cvt_pk_bf16_f32 v63, v64, v65
	v_cvt_pk_bf16_f32 v64, v58, v59
	v_cvt_pk_bf16_f32 v65, v60, v61
	s_nop 0
	global_store_dwordx4 v[66:67], v[62:65], off sc1
	s_nop 1
	v_cvt_pk_bf16_f32 v50, v50, v51
	v_cvt_pk_bf16_f32 v51, v52, v53
	v_cvt_pk_bf16_f32 v52, v42, v43
	v_lshl_add_u64 v[42:43], v[146:147], 0, s[28:29]
	s_mov_b64 s[28:29], 0x48000
	v_cvt_pk_bf16_f32 v53, v44, v45
	s_nop 0
	global_store_dwordx4 v[42:43], v[50:53], off sc1
	s_nop 1
	v_lshl_add_u64 v[50:51], v[146:147], 0, s[28:29]
	s_mov_b64 s[28:29], 0x48100
	v_cvt_pk_bf16_f32 v42, v54, v55
	v_cvt_pk_bf16_f32 v43, v56, v57
	v_cvt_pk_bf16_f32 v44, v46, v47
	v_cvt_pk_bf16_f32 v45, v48, v49
	s_nop 0
	global_store_dwordx4 v[50:51], v[42:45], off sc1
	s_nop 1
	v_cvt_pk_bf16_f32 v34, v34, v35
	v_cvt_pk_bf16_f32 v35, v36, v37
	v_cvt_pk_bf16_f32 v36, v26, v27
	v_lshl_add_u64 v[26:27], v[146:147], 0, s[28:29]
	s_mov_b64 s[28:29], 0x50000
	v_cvt_pk_bf16_f32 v37, v28, v29
	s_nop 0
	global_store_dwordx4 v[26:27], v[34:37], off sc1
	s_nop 1
	v_lshl_add_u64 v[34:35], v[146:147], 0, s[28:29]
	s_mov_b64 s[28:29], 0x50100
	v_cvt_pk_bf16_f32 v26, v38, v39
	v_cvt_pk_bf16_f32 v27, v40, v41
	v_cvt_pk_bf16_f32 v28, v30, v31
	v_cvt_pk_bf16_f32 v29, v32, v33
	s_nop 0
	global_store_dwordx4 v[34:35], v[26:29], off sc1
	s_nop 1
	v_cvt_pk_bf16_f32 v18, v18, v19
	v_cvt_pk_bf16_f32 v19, v20, v21
	v_cvt_pk_bf16_f32 v20, v10, v11
	v_lshl_add_u64 v[10:11], v[146:147], 0, s[28:29]
	v_cvt_pk_bf16_f32 v21, v12, v13
	s_mov_b64 s[28:29], s[22:23]
	global_store_dwordx4 v[10:11], v[18:21], off sc1
	s_nop 1
	v_lshl_add_u64 v[18:19], v[146:147], 0, s[12:13]
	v_cvt_pk_bf16_f32 v10, v22, v23
	v_cvt_pk_bf16_f32 v11, v24, v25
	v_cvt_pk_bf16_f32 v12, v14, v15
	v_cvt_pk_bf16_f32 v13, v16, v17
	s_nop 0
	global_store_dwordx4 v[18:19], v[10:13], off sc1
	s_nop 1
	v_cvt_pk_bf16_f32 v6, v6, v7
	v_cvt_pk_bf16_f32 v7, v8, v9
	v_cvt_pk_bf16_f32 v8, v2, v3
	v_cvt_pk_bf16_f32 v9, v4, v5
	v_lshl_add_u64 v[2:3], v[146:147], 0, s[14:15]
	global_store_dwordx4 v[2:3], v[6:9], off sc1
	s_nop 1
	s_cbranch_vccz .LBB0_93
	s_waitcnt vmcnt(0)
	s_cmpk_gt_u32 s2, 0xff
	s_cbranch_scc1 .LBB0_104
	s_barrier

.LBB0_105:
	s_setprio 0
	s_cmp_gt_i32 s67, 2
	s_cselect_b64 s[0:1], -1, 0
	s_and_b64 s[2:3], s[6:7], s[0:1]
	s_andn2_b64 vcc, exec, s[2:3]
	s_cbranch_vccnz .LBB0_159
	s_waitcnt vmcnt(0)
	s_waitcnt vmcnt(0)
	s_barrier
	s_and_saveexec_b64 s[4:5], s[96:97]
	s_cbranch_execz .LBB0_158
	s_add_i32 s2, 0, 0x26960
	v_mov_b32_e32 v1, s2
	s_waitcnt vmcnt(0) expcnt(0) lgkmcnt(0)
	ds_read_b32 v3, v1
	s_add_i32 s2, 0, 0x26964
	v_mov_b32_e32 v1, s2
	ds_read_b32 v1, v1
	s_waitcnt lgkmcnt(1)
	v_cmp_ne_u32_e32 vcc, 0, v3
	s_cbranch_vccnz .LBB0_122
	v_readlane_b32 s6, v253, 0
	v_readlane_b32 s7, v253, 1
	s_load_dwordx2 s[2:3], s[6:7], 0x4
	s_add_u32 s6, s86, 0x4200
	s_addc_u32 s7, s87, 0
	s_add_u32 s8, s86, 0x4400
	s_addc_u32 s9, s87, 0
	s_add_u32 s10, s86, 0x4500
	s_addc_u32 s11, s87, 0
	s_add_u32 s12, s86, 0x4600
	s_addc_u32 s13, s87, 0
	s_add_u32 s14, s86, 0x4700
	s_addc_u32 s15, s87, 0
	s_add_u32 s16, s86, 0x4800
	s_addc_u32 s17, s87, 0
	s_add_u32 s18, s86, 0x4900
	s_addc_u32 s19, s87, 0
	s_add_u32 s22, s86, 0x4a00
	s_addc_u32 s23, s87, 0
	s_add_u32 s24, s86, 0x4b00
	s_addc_u32 s25, s87, 0
	s_add_u32 s26, s86, 0x4c00
	s_addc_u32 s27, s87, 0
	s_add_u32 s28, s86, 0x4d00
	s_addc_u32 s29, s87, 0
	s_add_u32 s30, s86, 0x4e00
	s_addc_u32 s31, s87, 0
	s_add_u32 s34, s86, 0x4f00
	s_addc_u32 s35, s87, 0
	s_add_u32 s36, s86, 0x5000
	s_addc_u32 s37, s87, 0
	s_add_u32 s38, s86, 0x5100
	s_addc_u32 s39, s87, 0
	s_add_u32 s40, s86, 0x5200
	s_addc_u32 s41, s87, 0
	s_waitcnt lgkmcnt(0)
	s_mul_i32 s2, s2, s92
	s_add_u32 s42, s86, 0x5300
	s_mul_i32 s2, s2, s3
	s_addc_u32 s43, s87, 0
	s_mov_b32 s3, 1
	v_mov_b32_e32 v17, 0
	s_branch .LBB0_110

.LBB0_495:
	s_cmp_lt_i32 s66, 7
	s_cselect_b64 s[0:1], -1, 0
	s_add_u32 s2, s50, 0x6a00000
	s_addc_u32 s3, s51, 0
	s_and_b64 s[6:7], s[0:1], s[4:5]
	s_cmpk_eq_i32 s92, 0x100
	s_cselect_b64 s[0:1], -1, 0
	s_and_b64 s[4:5], s[6:7], s[0:1]
	s_andn2_b64 vcc, exec, s[4:5]
	s_cbranch_vccnz .LBB0_526
	s_lshl_b32 s4, s64, 2
	s_and_b32 s4, s4, 28
	s_ashr_i32 s5, s64, 6
	s_add_i32 s8, s4, s5
	s_cmp_gt_i32 s8, 63
	v_readfirstlane_b32 s4, v0
	s_cbranch_scc1 .LBB0_526
	s_cmpk_lt_u32 s4, 0x100
	s_cbranch_scc0 .Lsp_g2
	s_setprio 1
.Lsp_g2:
	v_lshrrev_b32_e32 v1, 5, v0
	s_waitcnt vmcnt(0)
	v_lshrrev_b32_e32 v3, 1, v0
	v_and_b32_e32 v1, 4, v1
	v_bfe_u32 v2, v0, 2, 2
	v_and_b32_e32 v3, 24, v3
	v_or3_b32 v1, v1, v2, v3
	v_lshlrev_b32_e32 v2, 4, v0
	v_or_b32_e32 v10, 0x2000, v2
	v_lshrrev_b32_e32 v3, 7, v10
	s_movk_i32 s9, 0x60
	v_and_or_b32 v4, v3, s9, v1
	v_and_b32_e32 v5, 32, v0
	v_bfe_u32 v13, v0, 2, 4
	s_movk_i32 s9, 0x70
	s_lshr_b32 s16, s4, 6
	s_bfe_u32 s20, s64, 0x30003
	v_bitop3_b32 v11, v2, v5, 48 bitop3:0x6c
	v_and_b32_e32 v12, 64, v0
	v_and_or_b32 v3, v3, s9, v13
	s_ashr_i32 s9, s8, 31
	s_lshr_b32 s5, s4, 8
	s_lshl_b32 s30, s16, 10
	v_or_b32_e32 v2, v11, v12
	s_lshl_b64 s[12:13], s[8:9], 20
	s_lshl_b32 s22, s20, 20
	v_lshl_or_b32 v132, v3, 12, v2
	v_lshrrev_b32_e32 v3, 3, v0
	s_add_u32 s10, s28, s22
	v_and_or_b32 v1, v3, 32, v1
	s_addc_u32 s11, s29, 0
	s_add_i32 s9, s30, 0
	v_lshl_or_b32 v134, v1, 12, v2
	s_add_i32 m0, s9, 0x10000
	v_lshl_or_b32 v130, v4, 12, v2
	global_load_lds_dwordx4 v134, s[10:11]
	s_add_i32 m0, s9, 0x12000
	s_add_u32 s14, s10, 0x80000
	global_load_lds_dwordx4 v130, s[10:11]
	s_addc_u32 s15, s11, 0
	s_add_i32 m0, s9, 0x14000
	v_and_or_b32 v1, v3, 48, v13
	global_load_lds_dwordx4 v134, s[14:15]
	s_add_i32 m0, s9, 0x16000
	s_add_u32 s12, s90, s12
	s_addc_u32 s13, s91, s13
	s_add_i32 s33, s9, 0x2000
	v_lshl_or_b32 v136, v1, 12, v2
	global_load_lds_dwordx4 v130, s[14:15]
	s_mov_b32 m0, s9
	s_add_u32 s14, s12, 0x80000
	global_load_lds_dwordx4 v136, s[12:13]
	s_mov_b32 m0, s33
	s_addc_u32 s15, s13, 0
	s_add_i32 s42, s9, 0x4000
	global_load_lds_dwordx4 v132, s[12:13]
	s_mov_b32 m0, s42
	s_add_i32 s43, s9, 0x6000
	global_load_lds_dwordx4 v136, s[14:15]
	s_mov_b32 m0, s43
	v_mov_b32_e32 v135, 0
	global_load_lds_dwordx4 v132, s[14:15]
	v_mov_b32_e32 v131, v135
	v_mov_b32_e32 v137, v135
	v_mov_b32_e32 v133, v135
	s_cmp_eq_u32 s5, 1
	s_mov_b32 s44, 0
	v_lshl_add_u64 v[8:9], s[10:11], 0, v[134:135]
	v_lshl_add_u64 v[6:7], s[10:11], 0, v[130:131]
	v_lshl_add_u64 v[2:3], s[12:13], 0, v[136:137]
	s_cselect_b64 s[14:15], -1, 0
	s_cmp_lg_u32 s5, 1
	v_lshl_add_u64 v[4:5], s[12:13], 0, v[132:133]
	s_cbranch_scc1 .LBB0_499
	s_barrier

.LBB0_503:
	ds_read_b128 v[152:155], v139
	ds_read_b128 v[156:159], v139 offset:1024
	ds_read_b128 v[160:163], v139 offset:2048
	ds_read_b128 v[164:167], v139 offset:3072
	ds_read_b128 v[172:175], v146
	ds_read_b128 v[176:179], v146 offset:1024
	ds_read_b128 v[180:183], v146 offset:2048
	ds_read_b128 v[184:187], v146 offset:3072
	s_add_u32 s38, s34, 0xfff80080
	s_addc_u32 s39, s35, -1
	s_cmp_eq_u32 s61, 28
	s_cselect_b32 s41, s59, s39
	s_cselect_b32 s40, s60, s38
	s_cselect_b32 s39, s11, s37
	s_cselect_b32 s38, s10, s36
	s_mov_b32 m0, s47
	v_lshl_add_u64 v[144:145], s[34:35], 0, v[140:141]
	ds_read_b128 v[188:191], v147
	ds_read_b128 v[192:195], v147 offset:1024
	ds_read_b128 v[196:199], v147 offset:2048
	ds_read_b128 v[200:203], v147 offset:3072
	ds_read_b128 v[204:207], v147 offset:4096
	ds_read_b128 v[208:211], v147 offset:5120
	ds_read_b128 v[212:215], v147 offset:6144
	ds_read_b128 v[216:219], v147 offset:7168
	global_load_lds_dwordx4 v[144:145], off
	v_lshl_add_u64 v[144:145], s[34:35], 0, v[142:143]
	s_mov_b32 m0, s48
	s_nop 0
	global_load_lds_dwordx4 v[144:145], off
	s_waitcnt vmcnt(8)
	s_waitcnt lgkmcnt(0)
	s_barrier
	s_waitcnt lgkmcnt(0)
	v_mfma_f32_16x16x32_bf16 v[126:129], v[152:155], v[188:191], v[126:129]
	v_mfma_f32_16x16x32_bf16 v[122:125], v[160:163], v[188:191], v[122:125]
	v_mfma_f32_16x16x32_bf16 v[110:113], v[152:155], v[196:199], v[110:113]
	v_mfma_f32_16x16x32_bf16 v[106:109], v[160:163], v[196:199], v[106:109]
	v_mfma_f32_16x16x32_bf16 v[94:97], v[152:155], v[204:207], v[94:97]
	v_mfma_f32_16x16x32_bf16 v[90:93], v[160:163], v[204:207], v[90:93]
	v_mfma_f32_16x16x32_bf16 v[78:81], v[152:155], v[212:215], v[78:81]
	v_mfma_f32_16x16x32_bf16 v[74:77], v[160:163], v[212:215], v[74:77]
	v_mfma_f32_16x16x32_bf16 v[126:129], v[156:159], v[192:195], v[126:129]
	v_mfma_f32_16x16x32_bf16 v[122:125], v[164:167], v[192:195], v[122:125]
	v_mfma_f32_16x16x32_bf16 v[110:113], v[156:159], v[200:203], v[110:113]
	v_mfma_f32_16x16x32_bf16 v[106:109], v[164:167], v[200:203], v[106:109]
	v_mfma_f32_16x16x32_bf16 v[94:97], v[156:159], v[208:211], v[94:97]
	v_mfma_f32_16x16x32_bf16 v[90:93], v[164:167], v[208:211], v[90:93]
	v_mfma_f32_16x16x32_bf16 v[78:81], v[156:159], v[216:219], v[78:81]
	v_mfma_f32_16x16x32_bf16 v[74:77], v[164:167], v[216:219], v[74:77]
	v_mfma_f32_16x16x32_bf16 v[118:121], v[172:175], v[188:191], v[118:121]
	v_mfma_f32_16x16x32_bf16 v[114:117], v[180:183], v[188:191], v[114:117]
	v_mfma_f32_16x16x32_bf16 v[102:105], v[172:175], v[196:199], v[102:105]
	v_mfma_f32_16x16x32_bf16 v[98:101], v[180:183], v[196:199], v[98:101]
	v_mfma_f32_16x16x32_bf16 v[86:89], v[172:175], v[204:207], v[86:89]
	v_mfma_f32_16x16x32_bf16 v[82:85], v[180:183], v[204:207], v[82:85]
	v_mfma_f32_16x16x32_bf16 v[70:73], v[172:175], v[212:215], v[70:73]
	v_mfma_f32_16x16x32_bf16 v[66:69], v[180:183], v[212:215], v[66:69]
	v_mfma_f32_16x16x32_bf16 v[118:121], v[176:179], v[192:195], v[118:121]
	v_mfma_f32_16x16x32_bf16 v[114:117], v[184:187], v[192:195], v[114:117]
	v_mfma_f32_16x16x32_bf16 v[102:105], v[176:179], v[200:203], v[102:105]
	v_mfma_f32_16x16x32_bf16 v[98:101], v[184:187], v[200:203], v[98:101]
	v_mfma_f32_16x16x32_bf16 v[86:89], v[176:179], v[208:211], v[86:89]
	v_mfma_f32_16x16x32_bf16 v[82:85], v[184:187], v[208:211], v[82:85]
	v_mfma_f32_16x16x32_bf16 v[70:73], v[176:179], v[216:219], v[70:73]
	v_mfma_f32_16x16x32_bf16 v[66:69], v[184:187], v[216:219], v[66:69]
	s_barrier
	s_mov_b32 m0, s49
	v_lshl_add_u64 v[144:145], s[38:39], 0, v[134:135]
	s_add_u32 s62, s38, 0x80000
	ds_read_b128 v[188:191], v147 offset:16384
	ds_read_b128 v[192:195], v147 offset:17408
	ds_read_b128 v[196:199], v147 offset:18432
	ds_read_b128 v[200:203], v147 offset:19456
	ds_read_b128 v[204:207], v147 offset:20480
	ds_read_b128 v[208:211], v147 offset:21504
	ds_read_b128 v[212:215], v147 offset:22528
	ds_read_b128 v[216:219], v147 offset:23552
	global_load_lds_dwordx4 v[144:145], off
	v_lshl_add_u64 v[168:169], s[38:39], 0, v[130:131]
	s_mov_b32 m0, s50
	s_addc_u32 s63, s39, 0
	global_load_lds_dwordx4 v[168:169], off
	v_lshl_add_u64 v[220:221], s[62:63], 0, v[134:135]
	s_mov_b32 m0, s51
	v_lshl_add_u64 v[222:223], s[40:41], 0, v[132:133]
	global_load_lds_dwordx4 v[220:221], off
	v_lshl_add_u64 v[220:221], s[62:63], 0, v[130:131]
	s_mov_b32 m0, s52
	s_nop 0
	global_load_lds_dwordx4 v[220:221], off
	v_lshl_add_u64 v[220:221], s[40:41], 0, v[136:137]
	s_mov_b32 m0, s9
	s_nop 0
	global_load_lds_dwordx4 v[220:221], off
	s_mov_b32 m0, s33
	s_nop 0
	global_load_lds_dwordx4 v[222:223], off
	s_waitcnt vmcnt(8)
	s_waitcnt lgkmcnt(0)
	s_barrier
	s_waitcnt lgkmcnt(0)
	v_mfma_f32_16x16x32_bf16 v[62:65], v[152:155], v[188:191], v[62:65]
	v_mfma_f32_16x16x32_bf16 v[58:61], v[160:163], v[188:191], v[58:61]
	v_mfma_f32_16x16x32_bf16 v[46:49], v[152:155], v[196:199], v[46:49]
	v_mfma_f32_16x16x32_bf16 v[42:45], v[160:163], v[196:199], v[42:45]
	v_mfma_f32_16x16x32_bf16 v[30:33], v[152:155], v[204:207], v[30:33]
	v_mfma_f32_16x16x32_bf16 v[26:29], v[160:163], v[204:207], v[26:29]
	v_mfma_f32_16x16x32_bf16 v[14:17], v[152:155], v[212:215], v[14:17]
	v_mfma_f32_16x16x32_bf16 v[10:13], v[160:163], v[212:215], v[10:13]
	v_mfma_f32_16x16x32_bf16 v[62:65], v[156:159], v[192:195], v[62:65]
	v_mfma_f32_16x16x32_bf16 v[58:61], v[164:167], v[192:195], v[58:61]
	v_mfma_f32_16x16x32_bf16 v[46:49], v[156:159], v[200:203], v[46:49]
	v_mfma_f32_16x16x32_bf16 v[42:45], v[164:167], v[200:203], v[42:45]
	v_mfma_f32_16x16x32_bf16 v[30:33], v[156:159], v[208:211], v[30:33]
	v_mfma_f32_16x16x32_bf16 v[26:29], v[164:167], v[208:211], v[26:29]
	v_mfma_f32_16x16x32_bf16 v[14:17], v[156:159], v[216:219], v[14:17]
	v_mfma_f32_16x16x32_bf16 v[10:13], v[164:167], v[216:219], v[10:13]
	v_mfma_f32_16x16x32_bf16 v[54:57], v[172:175], v[188:191], v[54:57]
	v_mfma_f32_16x16x32_bf16 v[50:53], v[180:183], v[188:191], v[50:53]
	v_mfma_f32_16x16x32_bf16 v[38:41], v[172:175], v[196:199], v[38:41]
	v_mfma_f32_16x16x32_bf16 v[34:37], v[180:183], v[196:199], v[34:37]
	v_mfma_f32_16x16x32_bf16 v[22:25], v[172:175], v[204:207], v[22:25]
	v_mfma_f32_16x16x32_bf16 v[18:21], v[180:183], v[204:207], v[18:21]
	v_mfma_f32_16x16x32_bf16 v[6:9], v[172:175], v[212:215], v[6:9]
	v_mfma_f32_16x16x32_bf16 v[2:5], v[180:183], v[212:215], v[2:5]
	v_mfma_f32_16x16x32_bf16 v[54:57], v[176:179], v[192:195], v[54:57]
	v_mfma_f32_16x16x32_bf16 v[50:53], v[184:187], v[192:195], v[50:53]
	v_mfma_f32_16x16x32_bf16 v[38:41], v[176:179], v[200:203], v[38:41]
	v_mfma_f32_16x16x32_bf16 v[34:37], v[184:187], v[200:203], v[34:37]
	v_mfma_f32_16x16x32_bf16 v[22:25], v[176:179], v[208:211], v[22:25]
	v_mfma_f32_16x16x32_bf16 v[18:21], v[184:187], v[208:211], v[18:21]
	v_mfma_f32_16x16x32_bf16 v[6:9], v[176:179], v[216:219], v[6:9]
	v_mfma_f32_16x16x32_bf16 v[2:5], v[184:187], v[216:219], v[2:5]
	s_barrier
	ds_read_b128 v[152:155], v149
	ds_read_b128 v[156:159], v149 offset:1024
	ds_read_b128 v[160:163], v149 offset:2048
	ds_read_b128 v[164:167], v149 offset:3072
	ds_read_b128 v[172:175], v150
	ds_read_b128 v[176:179], v150 offset:1024
	ds_read_b128 v[180:183], v150 offset:2048
	ds_read_b128 v[184:187], v150 offset:3072
	s_add_u32 s40, s40, 0x80000
	s_addc_u32 s41, s41, 0
	s_mov_b32 m0, s42
	v_lshl_add_u64 v[224:225], s[40:41], 0, v[136:137]
	ds_read_b128 v[188:191], v147 offset:32768
	ds_read_b128 v[192:195], v147 offset:33792
	ds_read_b128 v[196:199], v147 offset:34816
	ds_read_b128 v[200:203], v147 offset:35840
	ds_read_b128 v[204:207], v147 offset:36864
	ds_read_b128 v[208:211], v147 offset:37888
	ds_read_b128 v[212:215], v147 offset:38912
	ds_read_b128 v[216:219], v147 offset:39936
	global_load_lds_dwordx4 v[224:225], off
	v_lshl_add_u64 v[224:225], s[40:41], 0, v[132:133]
	s_mov_b32 m0, s43
	s_nop 0
	global_load_lds_dwordx4 v[224:225], off
	s_waitcnt vmcnt(8)
	s_waitcnt lgkmcnt(0)
	s_barrier
	s_waitcnt lgkmcnt(0)
	v_mfma_f32_16x16x32_bf16 v[126:129], v[152:155], v[188:191], v[126:129]
	v_mfma_f32_16x16x32_bf16 v[122:125], v[160:163], v[188:191], v[122:125]
	v_mfma_f32_16x16x32_bf16 v[110:113], v[152:155], v[196:199], v[110:113]
	v_mfma_f32_16x16x32_bf16 v[106:109], v[160:163], v[196:199], v[106:109]
	v_mfma_f32_16x16x32_bf16 v[94:97], v[152:155], v[204:207], v[94:97]
	v_mfma_f32_16x16x32_bf16 v[90:93], v[160:163], v[204:207], v[90:93]
	v_mfma_f32_16x16x32_bf16 v[78:81], v[152:155], v[212:215], v[78:81]
	v_mfma_f32_16x16x32_bf16 v[74:77], v[160:163], v[212:215], v[74:77]
	v_mfma_f32_16x16x32_bf16 v[126:129], v[156:159], v[192:195], v[126:129]
	v_mfma_f32_16x16x32_bf16 v[122:125], v[164:167], v[192:195], v[122:125]
	v_mfma_f32_16x16x32_bf16 v[110:113], v[156:159], v[200:203], v[110:113]
	v_mfma_f32_16x16x32_bf16 v[106:109], v[164:167], v[200:203], v[106:109]
	v_mfma_f32_16x16x32_bf16 v[94:97], v[156:159], v[208:211], v[94:97]
	v_mfma_f32_16x16x32_bf16 v[90:93], v[164:167], v[208:211], v[90:93]
	v_mfma_f32_16x16x32_bf16 v[78:81], v[156:159], v[216:219], v[78:81]
	v_mfma_f32_16x16x32_bf16 v[74:77], v[164:167], v[216:219], v[74:77]
	v_mfma_f32_16x16x32_bf16 v[118:121], v[172:175], v[188:191], v[118:121]
	v_mfma_f32_16x16x32_bf16 v[114:117], v[180:183], v[188:191], v[114:117]
	v_mfma_f32_16x16x32_bf16 v[102:105], v[172:175], v[196:199], v[102:105]
	v_mfma_f32_16x16x32_bf16 v[98:101], v[180:183], v[196:199], v[98:101]
	v_mfma_f32_16x16x32_bf16 v[86:89], v[172:175], v[204:207], v[86:89]
	v_mfma_f32_16x16x32_bf16 v[82:85], v[180:183], v[204:207], v[82:85]
	v_mfma_f32_16x16x32_bf16 v[70:73], v[172:175], v[212:215], v[70:73]
	v_mfma_f32_16x16x32_bf16 v[66:69], v[180:183], v[212:215], v[66:69]
	v_mfma_f32_16x16x32_bf16 v[118:121], v[176:179], v[192:195], v[118:121]
	v_mfma_f32_16x16x32_bf16 v[114:117], v[184:187], v[192:195], v[114:117]
	v_mfma_f32_16x16x32_bf16 v[102:105], v[176:179], v[200:203], v[102:105]
	v_mfma_f32_16x16x32_bf16 v[98:101], v[184:187], v[200:203], v[98:101]
	v_mfma_f32_16x16x32_bf16 v[86:89], v[176:179], v[208:211], v[86:89]
	v_mfma_f32_16x16x32_bf16 v[82:85], v[184:187], v[208:211], v[82:85]
	v_mfma_f32_16x16x32_bf16 v[70:73], v[176:179], v[216:219], v[70:73]
	v_mfma_f32_16x16x32_bf16 v[66:69], v[184:187], v[216:219], v[66:69]
	s_barrier
	s_mov_b32 m0, s53
	v_lshl_add_u64 v[144:145], v[144:145], 0, s[16:17]
	s_add_u32 s38, s38, 0x80080
	ds_read_b128 v[188:191], v147 offset:49152
	ds_read_b128 v[192:195], v147 offset:50176
	ds_read_b128 v[196:199], v147 offset:51200
	ds_read_b128 v[200:203], v147 offset:52224
	ds_read_b128 v[204:207], v147 offset:53248
	ds_read_b128 v[208:211], v147 offset:54272
	ds_read_b128 v[212:215], v147 offset:55296
	ds_read_b128 v[216:219], v147 offset:56320
	global_load_lds_dwordx4 v[144:145], off
	v_lshl_add_u64 v[144:145], v[168:169], 0, s[16:17]
	s_mov_b32 m0, s54
	s_addc_u32 s39, s39, 0
	global_load_lds_dwordx4 v[144:145], off
	v_lshl_add_u64 v[144:145], s[38:39], 0, v[134:135]
	s_mov_b32 m0, s55
	s_nop 0
	global_load_lds_dwordx4 v[144:145], off
	v_lshl_add_u64 v[144:145], s[38:39], 0, v[130:131]
	s_mov_b32 m0, s56
	s_nop 0
	global_load_lds_dwordx4 v[144:145], off
	v_lshl_add_u64 v[144:145], v[220:221], 0, s[16:17]
	s_mov_b32 m0, s45
	s_nop 0
	global_load_lds_dwordx4 v[144:145], off
	v_lshl_add_u64 v[144:145], v[222:223], 0, s[16:17]
	s_mov_b32 m0, s46
	s_nop 0
	global_load_lds_dwordx4 v[144:145], off
	s_waitcnt vmcnt(8)
	s_waitcnt lgkmcnt(0)
	s_barrier
	s_waitcnt lgkmcnt(0)
	v_mfma_f32_16x16x32_bf16 v[62:65], v[152:155], v[188:191], v[62:65]
	v_mfma_f32_16x16x32_bf16 v[58:61], v[160:163], v[188:191], v[58:61]
	v_mfma_f32_16x16x32_bf16 v[46:49], v[152:155], v[196:199], v[46:49]
	v_mfma_f32_16x16x32_bf16 v[42:45], v[160:163], v[196:199], v[42:45]
	v_mfma_f32_16x16x32_bf16 v[30:33], v[152:155], v[204:207], v[30:33]
	v_mfma_f32_16x16x32_bf16 v[26:29], v[160:163], v[204:207], v[26:29]
	v_mfma_f32_16x16x32_bf16 v[14:17], v[152:155], v[212:215], v[14:17]
	v_mfma_f32_16x16x32_bf16 v[10:13], v[160:163], v[212:215], v[10:13]
	v_mfma_f32_16x16x32_bf16 v[62:65], v[156:159], v[192:195], v[62:65]
	v_mfma_f32_16x16x32_bf16 v[58:61], v[164:167], v[192:195], v[58:61]
	v_mfma_f32_16x16x32_bf16 v[46:49], v[156:159], v[200:203], v[46:49]
	v_mfma_f32_16x16x32_bf16 v[42:45], v[164:167], v[200:203], v[42:45]
	v_mfma_f32_16x16x32_bf16 v[30:33], v[156:159], v[208:211], v[30:33]
	v_mfma_f32_16x16x32_bf16 v[26:29], v[164:167], v[208:211], v[26:29]
	v_mfma_f32_16x16x32_bf16 v[14:17], v[156:159], v[216:219], v[14:17]
	v_mfma_f32_16x16x32_bf16 v[10:13], v[164:167], v[216:219], v[10:13]
	v_mfma_f32_16x16x32_bf16 v[54:57], v[172:175], v[188:191], v[54:57]
	v_mfma_f32_16x16x32_bf16 v[50:53], v[180:183], v[188:191], v[50:53]
	v_mfma_f32_16x16x32_bf16 v[38:41], v[172:175], v[196:199], v[38:41]
	v_mfma_f32_16x16x32_bf16 v[34:37], v[180:183], v[196:199], v[34:37]
	v_mfma_f32_16x16x32_bf16 v[22:25], v[172:175], v[204:207], v[22:25]
	v_mfma_f32_16x16x32_bf16 v[18:21], v[180:183], v[204:207], v[18:21]
	v_mfma_f32_16x16x32_bf16 v[6:9], v[172:175], v[212:215], v[6:9]
	v_mfma_f32_16x16x32_bf16 v[2:5], v[180:183], v[212:215], v[2:5]
	v_mfma_f32_16x16x32_bf16 v[54:57], v[176:179], v[192:195], v[54:57]
	v_mfma_f32_16x16x32_bf16 v[50:53], v[184:187], v[192:195], v[50:53]
	v_mfma_f32_16x16x32_bf16 v[38:41], v[176:179], v[200:203], v[38:41]
	v_mfma_f32_16x16x32_bf16 v[34:37], v[184:187], v[200:203], v[34:37]
	v_mfma_f32_16x16x32_bf16 v[22:25], v[176:179], v[208:211], v[22:25]
	v_mfma_f32_16x16x32_bf16 v[18:21], v[184:187], v[208:211], v[18:21]
	v_mfma_f32_16x16x32_bf16 v[6:9], v[176:179], v[216:219], v[6:9]
	v_mfma_f32_16x16x32_bf16 v[2:5], v[184:187], v[216:219], v[2:5]
	s_barrier
	s_add_i32 s61, s61, 2
	s_add_u32 s34, s34, 0x100
	s_addc_u32 s35, s35, 0
	s_add_u32 s36, s36, 0x100
	s_addc_u32 s37, s37, 0
	s_cmp_gt_u32 s61, 29
	s_cbranch_scc0 .LBB0_503
	s_and_b64 vcc, exec, s[18:19]
	s_cbranch_vccz .LBB0_506
	s_barrier

.LBB0_526:
	s_setprio 0
	s_cmp_gt_i32 s67, 7
	s_cselect_b64 s[4:5], -1, 0
	s_and_b64 s[6:7], s[6:7], s[4:5]
	s_andn2_b64 vcc, exec, s[6:7]
	s_cbranch_vccnz .LBB0_580
	s_waitcnt vmcnt(0)
	s_waitcnt vmcnt(0) lgkmcnt(0)
	s_barrier
	s_and_saveexec_b64 s[6:7], s[96:97]
	s_cbranch_execz .LBB0_579
	s_add_i32 s8, 0, 0x26960
	v_mov_b32_e32 v1, s8
	s_waitcnt vmcnt(0) expcnt(0) lgkmcnt(0)
	ds_read_b32 v3, v1
	s_add_i32 s8, 0, 0x26964
	v_mov_b32_e32 v1, s8
	ds_read_b32 v1, v1
	s_waitcnt lgkmcnt(1)
	v_cmp_ne_u32_e32 vcc, 0, v3
	s_cbranch_vccnz .LBB0_543
	v_readlane_b32 s8, v253, 0
	v_readlane_b32 s9, v253, 1
	s_load_dwordx2 s[12:13], s[8:9], 0x4
	s_add_u32 s8, s50, 0x4200
	s_addc_u32 s9, s51, 0
	s_add_u32 s10, s50, 0x4400
	s_addc_u32 s11, s51, 0
	s_waitcnt lgkmcnt(0)
	s_mul_i32 s33, s12, s92
	s_add_u32 s12, s50, 0x4500
	s_mul_i32 s33, s33, s13
	s_addc_u32 s13, s51, 0
	s_add_u32 s14, s50, 0x4600
	s_addc_u32 s15, s51, 0
	s_add_u32 s16, s50, 0x4700
	s_addc_u32 s17, s51, 0
	s_add_u32 s18, s50, 0x4800
	s_addc_u32 s19, s51, 0
	s_add_u32 s20, s50, 0x4900
	s_addc_u32 s21, s51, 0
	s_add_u32 s22, s50, 0x4a00
	s_addc_u32 s23, s51, 0
	s_add_u32 s28, s50, 0x4b00
	s_addc_u32 s29, s51, 0
	s_add_u32 s30, s50, 0x4c00
	s_addc_u32 s31, s51, 0
	s_add_u32 s34, s50, 0x4d00
	s_addc_u32 s35, s51, 0
	s_add_u32 s36, s50, 0x4e00
	s_addc_u32 s37, s51, 0
	s_add_u32 s38, s50, 0x4f00
	s_addc_u32 s39, s51, 0
	s_add_u32 s40, s50, 0x5000
	s_addc_u32 s41, s51, 0
	s_add_u32 s42, s50, 0x5100
	s_addc_u32 s43, s51, 0
	s_add_u32 s44, s50, 0x5200
	s_addc_u32 s45, s51, 0
	s_add_u32 s46, s50, 0x5300
	s_addc_u32 s47, s51, 0
	s_mov_b32 s54, 1
	v_mov_b32_e32 v17, 0
	s_branch .LBB0_531

.LBB0_580:
	s_cmp_lt_i32 s66, 8
	s_cselect_b64 s[6:7], -1, 0
	s_and_b64 s[8:9], s[6:7], s[4:5]
	s_andn2_b64 vcc, exec, s[8:9]
	s_cbranch_vccnz .LBB0_643
	v_readfirstlane_b32 s98, v0
	s_cmpk_lt_u32 s98, 0x100
	s_cbranch_scc0 .Lsp_g3
	s_setprio 1
.Lsp_g3:
	s_cmpk_lt_i32 s64, 0x800
	s_cselect_b64 s[6:7], -1, 0
	s_cmpk_gt_i32 s64, 0x7ff
	s_cbranch_scc1 .LBB0_584
	s_ashr_i32 s4, s64, 31
	s_lshr_b32 s4, s4, 29
	s_add_i32 s10, s64, s4
	s_and_b32 s4, s10, -8
	s_sub_i32 s11, s64, s4
	s_cmp_gt_i32 s11, -1
	s_cbranch_scc0 .LBB0_585
	s_lshl_b32 s12, s11, 8
	s_cbranch_execz .LBB0_586
	s_branch .LBB0_587

.LBB0_607:
	ds_read_b128 v[148:151], v155
	ds_read_b128 v[160:163], v155 offset:1024
	ds_read_b128 v[164:167], v155 offset:2048
	ds_read_b128 v[172:175], v155 offset:3072
	ds_read_b128 v[176:179], v156
	ds_read_b128 v[180:183], v156 offset:1024
	ds_read_b128 v[184:187], v156 offset:2048
	ds_read_b128 v[188:191], v156 offset:3072
	s_add_u32 s30, s4, 0xfff80080
	s_addc_u32 s31, s5, -1
	s_cmp_eq_u32 s49, 28
	s_cselect_b32 s35, s17, s31
	s_cselect_b32 s34, s23, s30
	s_cselect_b32 s31, s15, s48
	s_cselect_b32 s30, s29, s47
	v_lshl_add_u64 v[168:169], s[4:5], 0, v[140:141]
	s_add_i32 m0, s36, 0xc000
	ds_read_b128 v[192:195], v157
	ds_read_b128 v[196:199], v157 offset:1024
	ds_read_b128 v[200:203], v157 offset:2048
	ds_read_b128 v[204:207], v157 offset:3072
	ds_read_b128 v[208:211], v157 offset:4096
	ds_read_b128 v[212:215], v157 offset:5120
	ds_read_b128 v[216:219], v157 offset:6144
	ds_read_b128 v[220:223], v157 offset:7168
	global_load_lds_dwordx4 v[168:169], off
	v_lshl_add_u64 v[168:169], s[4:5], 0, v[142:143]
	s_add_i32 m0, s36, 0xe000
	s_nop 0
	global_load_lds_dwordx4 v[168:169], off
	s_waitcnt vmcnt(8)
	s_waitcnt lgkmcnt(0)
	s_barrier
	s_waitcnt lgkmcnt(0)
	v_mfma_f32_16x16x32_bf16 v[126:129], v[148:151], v[192:195], v[126:129]
	v_mfma_f32_16x16x32_bf16 v[122:125], v[164:167], v[192:195], v[122:125]
	v_mfma_f32_16x16x32_bf16 v[110:113], v[148:151], v[200:203], v[110:113]
	v_mfma_f32_16x16x32_bf16 v[106:109], v[164:167], v[200:203], v[106:109]
	v_mfma_f32_16x16x32_bf16 v[94:97], v[148:151], v[208:211], v[94:97]
	v_mfma_f32_16x16x32_bf16 v[90:93], v[164:167], v[208:211], v[90:93]
	v_mfma_f32_16x16x32_bf16 v[78:81], v[148:151], v[216:219], v[78:81]
	v_mfma_f32_16x16x32_bf16 v[74:77], v[164:167], v[216:219], v[74:77]
	v_mfma_f32_16x16x32_bf16 v[126:129], v[160:163], v[196:199], v[126:129]
	v_mfma_f32_16x16x32_bf16 v[122:125], v[172:175], v[196:199], v[122:125]
	v_mfma_f32_16x16x32_bf16 v[110:113], v[160:163], v[204:207], v[110:113]
	v_mfma_f32_16x16x32_bf16 v[106:109], v[172:175], v[204:207], v[106:109]
	v_mfma_f32_16x16x32_bf16 v[94:97], v[160:163], v[212:215], v[94:97]
	v_mfma_f32_16x16x32_bf16 v[90:93], v[172:175], v[212:215], v[90:93]
	v_mfma_f32_16x16x32_bf16 v[78:81], v[160:163], v[220:223], v[78:81]
	v_mfma_f32_16x16x32_bf16 v[74:77], v[172:175], v[220:223], v[74:77]
	v_mfma_f32_16x16x32_bf16 v[118:121], v[176:179], v[192:195], v[118:121]
	v_mfma_f32_16x16x32_bf16 v[114:117], v[184:187], v[192:195], v[114:117]
	v_mfma_f32_16x16x32_bf16 v[102:105], v[176:179], v[200:203], v[102:105]
	v_mfma_f32_16x16x32_bf16 v[98:101], v[184:187], v[200:203], v[98:101]
	v_mfma_f32_16x16x32_bf16 v[86:89], v[176:179], v[208:211], v[86:89]
	v_mfma_f32_16x16x32_bf16 v[82:85], v[184:187], v[208:211], v[82:85]
	v_mfma_f32_16x16x32_bf16 v[70:73], v[176:179], v[216:219], v[70:73]
	v_mfma_f32_16x16x32_bf16 v[66:69], v[184:187], v[216:219], v[66:69]
	v_mfma_f32_16x16x32_bf16 v[118:121], v[180:183], v[196:199], v[118:121]
	v_mfma_f32_16x16x32_bf16 v[114:117], v[188:191], v[196:199], v[114:117]
	v_mfma_f32_16x16x32_bf16 v[102:105], v[180:183], v[204:207], v[102:105]
	v_mfma_f32_16x16x32_bf16 v[98:101], v[188:191], v[204:207], v[98:101]
	v_mfma_f32_16x16x32_bf16 v[86:89], v[180:183], v[212:215], v[86:89]
	v_mfma_f32_16x16x32_bf16 v[82:85], v[188:191], v[212:215], v[82:85]
	v_mfma_f32_16x16x32_bf16 v[70:73], v[180:183], v[220:223], v[70:73]
	v_mfma_f32_16x16x32_bf16 v[66:69], v[188:191], v[220:223], v[66:69]
	s_barrier
	s_add_i32 s50, s45, s33
	v_lshl_add_u64 v[168:169], s[30:31], 0, v[132:133]
	s_mov_b32 m0, s50
	ds_read_b128 v[192:195], v157 offset:16384
	ds_read_b128 v[196:199], v157 offset:17408
	ds_read_b128 v[200:203], v157 offset:18432
	ds_read_b128 v[204:207], v157 offset:19456
	ds_read_b128 v[208:211], v157 offset:20480
	ds_read_b128 v[212:215], v157 offset:21504
	ds_read_b128 v[216:219], v157 offset:22528
	ds_read_b128 v[220:223], v157 offset:23552
	global_load_lds_dwordx4 v[168:169], off
	s_add_i32 m0, s50, 0x2000
	s_add_u32 s50, s30, 0x80000
	v_lshl_add_u64 v[224:225], s[30:31], 0, v[136:137]
	s_addc_u32 s51, s31, 0
	s_add_i32 s52, s46, s33
	global_load_lds_dwordx4 v[224:225], off
	v_lshl_add_u64 v[226:227], s[50:51], 0, v[132:133]
	s_mov_b32 m0, s52
	v_lshl_add_u64 v[228:229], s[34:35], 0, v[134:135]
	global_load_lds_dwordx4 v[226:227], off
	v_lshl_add_u64 v[226:227], s[50:51], 0, v[136:137]
	s_add_i32 m0, s52, 0x2000
	s_nop 0
	global_load_lds_dwordx4 v[226:227], off
	v_lshl_add_u64 v[226:227], s[34:35], 0, v[130:131]
	s_mov_b32 m0, s36
	s_nop 0
	global_load_lds_dwordx4 v[226:227], off
	s_mov_b32 m0, s37
	s_nop 0
	global_load_lds_dwordx4 v[228:229], off
	s_waitcnt vmcnt(8)
	s_waitcnt lgkmcnt(0)
	s_barrier
	s_waitcnt lgkmcnt(0)
	v_mfma_f32_16x16x32_bf16 v[62:65], v[148:151], v[192:195], v[62:65]
	v_mfma_f32_16x16x32_bf16 v[58:61], v[164:167], v[192:195], v[58:61]
	v_mfma_f32_16x16x32_bf16 v[46:49], v[148:151], v[200:203], v[46:49]
	v_mfma_f32_16x16x32_bf16 v[42:45], v[164:167], v[200:203], v[42:45]
	v_mfma_f32_16x16x32_bf16 v[30:33], v[148:151], v[208:211], v[30:33]
	v_mfma_f32_16x16x32_bf16 v[26:29], v[164:167], v[208:211], v[26:29]
	v_mfma_f32_16x16x32_bf16 v[14:17], v[148:151], v[216:219], v[14:17]
	v_mfma_f32_16x16x32_bf16 v[10:13], v[164:167], v[216:219], v[10:13]
	v_mfma_f32_16x16x32_bf16 v[62:65], v[160:163], v[196:199], v[62:65]
	v_mfma_f32_16x16x32_bf16 v[58:61], v[172:175], v[196:199], v[58:61]
	v_mfma_f32_16x16x32_bf16 v[46:49], v[160:163], v[204:207], v[46:49]
	v_mfma_f32_16x16x32_bf16 v[42:45], v[172:175], v[204:207], v[42:45]
	v_mfma_f32_16x16x32_bf16 v[30:33], v[160:163], v[212:215], v[30:33]
	v_mfma_f32_16x16x32_bf16 v[26:29], v[172:175], v[212:215], v[26:29]
	v_mfma_f32_16x16x32_bf16 v[14:17], v[160:163], v[220:223], v[14:17]
	v_mfma_f32_16x16x32_bf16 v[10:13], v[172:175], v[220:223], v[10:13]
	v_mfma_f32_16x16x32_bf16 v[54:57], v[176:179], v[192:195], v[54:57]
	v_mfma_f32_16x16x32_bf16 v[50:53], v[184:187], v[192:195], v[50:53]
	v_mfma_f32_16x16x32_bf16 v[38:41], v[176:179], v[200:203], v[38:41]
	v_mfma_f32_16x16x32_bf16 v[34:37], v[184:187], v[200:203], v[34:37]
	v_mfma_f32_16x16x32_bf16 v[22:25], v[176:179], v[208:211], v[22:25]
	v_mfma_f32_16x16x32_bf16 v[18:21], v[184:187], v[208:211], v[18:21]
	v_mfma_f32_16x16x32_bf16 v[6:9], v[176:179], v[216:219], v[6:9]
	v_mfma_f32_16x16x32_bf16 v[2:5], v[184:187], v[216:219], v[2:5]
	v_mfma_f32_16x16x32_bf16 v[54:57], v[180:183], v[196:199], v[54:57]
	v_mfma_f32_16x16x32_bf16 v[50:53], v[188:191], v[196:199], v[50:53]
	v_mfma_f32_16x16x32_bf16 v[38:41], v[180:183], v[204:207], v[38:41]
	v_mfma_f32_16x16x32_bf16 v[34:37], v[188:191], v[204:207], v[34:37]
	v_mfma_f32_16x16x32_bf16 v[22:25], v[180:183], v[212:215], v[22:25]
	v_mfma_f32_16x16x32_bf16 v[18:21], v[188:191], v[212:215], v[18:21]
	v_mfma_f32_16x16x32_bf16 v[6:9], v[180:183], v[220:223], v[6:9]
	v_mfma_f32_16x16x32_bf16 v[2:5], v[188:191], v[220:223], v[2:5]
	s_barrier
	s_add_i32 s50, 0, 0x18000
	s_add_i32 s51, 0, 0x1c000
	v_add_u32_e32 v172, s50, v152
	v_add_u32_e32 v188, s51, v152
	ds_read_b128 v[148:151], v172
	ds_read_b128 v[160:163], v172 offset:1024
	ds_read_b128 v[164:167], v172 offset:2048
	ds_read_b128 v[172:175], v172 offset:3072
	ds_read_b128 v[176:179], v188
	ds_read_b128 v[180:183], v188 offset:1024
	ds_read_b128 v[184:187], v188 offset:2048
	ds_read_b128 v[188:191], v188 offset:3072
	s_add_u32 s34, s34, 0x80000
	s_addc_u32 s35, s35, 0
	s_mov_b32 m0, s38
	v_lshl_add_u64 v[230:231], s[34:35], 0, v[130:131]
	ds_read_b128 v[192:195], v157 offset:32768
	ds_read_b128 v[196:199], v157 offset:33792
	ds_read_b128 v[200:203], v157 offset:34816
	ds_read_b128 v[204:207], v157 offset:35840
	ds_read_b128 v[208:211], v157 offset:36864
	ds_read_b128 v[212:215], v157 offset:37888
	ds_read_b128 v[216:219], v157 offset:38912
	ds_read_b128 v[220:223], v157 offset:39936
	global_load_lds_dwordx4 v[230:231], off
	v_lshl_add_u64 v[230:231], s[34:35], 0, v[134:135]
	s_mov_b32 m0, s39
	s_nop 0
	global_load_lds_dwordx4 v[230:231], off
	s_waitcnt vmcnt(8)
	s_waitcnt lgkmcnt(0)
	s_barrier
	s_waitcnt lgkmcnt(0)
	v_mfma_f32_16x16x32_bf16 v[126:129], v[148:151], v[192:195], v[126:129]
	v_mfma_f32_16x16x32_bf16 v[122:125], v[164:167], v[192:195], v[122:125]
	v_mfma_f32_16x16x32_bf16 v[110:113], v[148:151], v[200:203], v[110:113]
	v_mfma_f32_16x16x32_bf16 v[106:109], v[164:167], v[200:203], v[106:109]
	v_mfma_f32_16x16x32_bf16 v[94:97], v[148:151], v[208:211], v[94:97]
	v_mfma_f32_16x16x32_bf16 v[90:93], v[164:167], v[208:211], v[90:93]
	v_mfma_f32_16x16x32_bf16 v[78:81], v[148:151], v[216:219], v[78:81]
	v_mfma_f32_16x16x32_bf16 v[74:77], v[164:167], v[216:219], v[74:77]
	v_mfma_f32_16x16x32_bf16 v[126:129], v[160:163], v[196:199], v[126:129]
	v_mfma_f32_16x16x32_bf16 v[122:125], v[172:175], v[196:199], v[122:125]
	v_mfma_f32_16x16x32_bf16 v[110:113], v[160:163], v[204:207], v[110:113]
	v_mfma_f32_16x16x32_bf16 v[106:109], v[172:175], v[204:207], v[106:109]
	v_mfma_f32_16x16x32_bf16 v[94:97], v[160:163], v[212:215], v[94:97]
	v_mfma_f32_16x16x32_bf16 v[90:93], v[172:175], v[212:215], v[90:93]
	v_mfma_f32_16x16x32_bf16 v[78:81], v[160:163], v[220:223], v[78:81]
	v_mfma_f32_16x16x32_bf16 v[74:77], v[172:175], v[220:223], v[74:77]
	v_mfma_f32_16x16x32_bf16 v[118:121], v[176:179], v[192:195], v[118:121]
	v_mfma_f32_16x16x32_bf16 v[114:117], v[184:187], v[192:195], v[114:117]
	v_mfma_f32_16x16x32_bf16 v[102:105], v[176:179], v[200:203], v[102:105]
	v_mfma_f32_16x16x32_bf16 v[98:101], v[184:187], v[200:203], v[98:101]
	v_mfma_f32_16x16x32_bf16 v[86:89], v[176:179], v[208:211], v[86:89]
	v_mfma_f32_16x16x32_bf16 v[82:85], v[184:187], v[208:211], v[82:85]
	v_mfma_f32_16x16x32_bf16 v[70:73], v[176:179], v[216:219], v[70:73]
	v_mfma_f32_16x16x32_bf16 v[66:69], v[184:187], v[216:219], v[66:69]
	v_mfma_f32_16x16x32_bf16 v[118:121], v[180:183], v[196:199], v[118:121]
	v_mfma_f32_16x16x32_bf16 v[114:117], v[188:191], v[196:199], v[114:117]
	v_mfma_f32_16x16x32_bf16 v[102:105], v[180:183], v[204:207], v[102:105]
	v_mfma_f32_16x16x32_bf16 v[98:101], v[188:191], v[204:207], v[98:101]
	v_mfma_f32_16x16x32_bf16 v[86:89], v[180:183], v[212:215], v[86:89]
	v_mfma_f32_16x16x32_bf16 v[82:85], v[188:191], v[212:215], v[82:85]
	v_mfma_f32_16x16x32_bf16 v[70:73], v[180:183], v[220:223], v[70:73]
	v_mfma_f32_16x16x32_bf16 v[66:69], v[188:191], v[220:223], v[66:69]
	s_barrier
	s_add_i32 s34, s50, s33
	v_lshl_add_u64 v[168:169], v[168:169], 0, s[12:13]
	s_mov_b32 m0, s34
	ds_read_b128 v[192:195], v157 offset:49152
	ds_read_b128 v[196:199], v157 offset:50176
	ds_read_b128 v[200:203], v157 offset:51200
	ds_read_b128 v[204:207], v157 offset:52224
	ds_read_b128 v[208:211], v157 offset:53248
	ds_read_b128 v[212:215], v157 offset:54272
	ds_read_b128 v[216:219], v157 offset:55296
	ds_read_b128 v[220:223], v157 offset:56320
	global_load_lds_dwordx4 v[168:169], off
	s_add_i32 m0, s34, 0x2000
	s_add_u32 s30, s30, 0x80080
	v_lshl_add_u64 v[168:169], v[224:225], 0, s[12:13]
	s_addc_u32 s31, s31, 0
	s_add_i32 s34, s51, s33
	global_load_lds_dwordx4 v[168:169], off
	v_lshl_add_u64 v[168:169], s[30:31], 0, v[132:133]
	s_mov_b32 m0, s34
	s_nop 0
	global_load_lds_dwordx4 v[168:169], off
	v_lshl_add_u64 v[168:169], s[30:31], 0, v[136:137]
	s_add_i32 m0, s34, 0x2000
	s_nop 0
	global_load_lds_dwordx4 v[168:169], off
	v_lshl_add_u64 v[168:169], v[226:227], 0, s[12:13]
	s_mov_b32 m0, s42
	s_nop 0
	global_load_lds_dwordx4 v[168:169], off
	v_lshl_add_u64 v[168:169], v[228:229], 0, s[12:13]
	s_mov_b32 m0, s43
	s_nop 0
	global_load_lds_dwordx4 v[168:169], off
	s_waitcnt vmcnt(8)
	s_waitcnt lgkmcnt(0)
	s_barrier
	s_waitcnt lgkmcnt(0)
	v_mfma_f32_16x16x32_bf16 v[62:65], v[148:151], v[192:195], v[62:65]
	v_mfma_f32_16x16x32_bf16 v[58:61], v[164:167], v[192:195], v[58:61]
	v_mfma_f32_16x16x32_bf16 v[46:49], v[148:151], v[200:203], v[46:49]
	v_mfma_f32_16x16x32_bf16 v[42:45], v[164:167], v[200:203], v[42:45]
	v_mfma_f32_16x16x32_bf16 v[30:33], v[148:151], v[208:211], v[30:33]
	v_mfma_f32_16x16x32_bf16 v[26:29], v[164:167], v[208:211], v[26:29]
	v_mfma_f32_16x16x32_bf16 v[14:17], v[148:151], v[216:219], v[14:17]
	v_mfma_f32_16x16x32_bf16 v[10:13], v[164:167], v[216:219], v[10:13]
	v_mfma_f32_16x16x32_bf16 v[62:65], v[160:163], v[196:199], v[62:65]
	v_mfma_f32_16x16x32_bf16 v[58:61], v[172:175], v[196:199], v[58:61]
	v_mfma_f32_16x16x32_bf16 v[46:49], v[160:163], v[204:207], v[46:49]
	v_mfma_f32_16x16x32_bf16 v[42:45], v[172:175], v[204:207], v[42:45]
	v_mfma_f32_16x16x32_bf16 v[30:33], v[160:163], v[212:215], v[30:33]
	v_mfma_f32_16x16x32_bf16 v[26:29], v[172:175], v[212:215], v[26:29]
	v_mfma_f32_16x16x32_bf16 v[14:17], v[160:163], v[220:223], v[14:17]
	v_mfma_f32_16x16x32_bf16 v[10:13], v[172:175], v[220:223], v[10:13]
	v_mfma_f32_16x16x32_bf16 v[54:57], v[176:179], v[192:195], v[54:57]
	v_mfma_f32_16x16x32_bf16 v[50:53], v[184:187], v[192:195], v[50:53]
	v_mfma_f32_16x16x32_bf16 v[38:41], v[176:179], v[200:203], v[38:41]
	v_mfma_f32_16x16x32_bf16 v[34:37], v[184:187], v[200:203], v[34:37]
	v_mfma_f32_16x16x32_bf16 v[22:25], v[176:179], v[208:211], v[22:25]
	v_mfma_f32_16x16x32_bf16 v[18:21], v[184:187], v[208:211], v[18:21]
	v_mfma_f32_16x16x32_bf16 v[6:9], v[176:179], v[216:219], v[6:9]
	v_mfma_f32_16x16x32_bf16 v[2:5], v[184:187], v[216:219], v[2:5]
	v_mfma_f32_16x16x32_bf16 v[54:57], v[180:183], v[196:199], v[54:57]
	v_mfma_f32_16x16x32_bf16 v[50:53], v[188:191], v[196:199], v[50:53]
	v_mfma_f32_16x16x32_bf16 v[38:41], v[180:183], v[204:207], v[38:41]
	v_mfma_f32_16x16x32_bf16 v[34:37], v[188:191], v[204:207], v[34:37]
	v_mfma_f32_16x16x32_bf16 v[22:25], v[180:183], v[212:215], v[22:25]
	v_mfma_f32_16x16x32_bf16 v[18:21], v[188:191], v[212:215], v[18:21]
	v_mfma_f32_16x16x32_bf16 v[6:9], v[180:183], v[220:223], v[6:9]
	v_mfma_f32_16x16x32_bf16 v[2:5], v[188:191], v[220:223], v[2:5]
	s_barrier
	s_add_i32 s49, s49, 2
	s_add_u32 s4, s4, 0x100
	s_addc_u32 s5, s5, 0
	s_add_u32 s47, s47, 0x100
	s_addc_u32 s48, s48, 0
	s_cmp_gt_u32 s49, 29
	s_cbranch_scc0 .LBB0_607
	s_cmp_lg_u32 s28, s10
	v_lshl_add_u32 v148, s28, 8, v1
	s_cselect_b64 s[28:29], -1, 0
	s_mov_b64 s[4:5], -1
	s_and_b64 vcc, exec, s[28:29]
	v_ashrrev_i32_e32 v149, 31, v148
	s_cbranch_vccz .LBB0_610
	v_lshlrev_b64 v[150:151], 7, v[148:149]
	v_lshl_add_u64 v[150:151], v[138:139], 0, v[150:151]
	global_load_dwordx4 v[160:163], v[150:151], off
	global_load_dwordx4 v[164:167], v[150:151], off offset:16
	v_and_b32_e32 v151, 64, v159
	v_xor_b32_e32 v150, 16, v159
	v_add_u32_e32 v168, 64, v151
	v_cmp_lt_i32_e32 vcc, v150, v168
	s_waitcnt vmcnt(0)
	v_mov_b32_e32 v151, v164
	v_cndmask_b32_e32 v150, v159, v150, vcc
	v_lshlrev_b32_e32 v169, 2, v150
	v_mov_b32_e32 v150, v160
	v_mov_b32_e32 v164, v161
	v_mov_b32_e32 v160, v162
	v_mov_b32_e32 v161, v166
	v_mov_b32_e32 v166, v163
	v_pk_add_f32 v[150:151], v[150:151], v[164:165]
	v_pk_add_f32 v[160:161], v[160:161], v[166:167]
	s_nop 0
	v_pk_add_f32 v[150:151], v[150:151], v[160:161]
	v_xor_b32_e32 v160, 32, v159
	v_add_f32_e32 v150, v150, v151
	ds_bpermute_b32 v151, v169, v150
	v_cmp_lt_i32_e32 vcc, v160, v168
	s_waitcnt lgkmcnt(0)
	v_add_f32_e32 v150, v150, v151
	v_cndmask_b32_e32 v160, v159, v160, vcc
	v_lshlrev_b32_e32 v160, 2, v160
	ds_bpermute_b32 v151, v160, v150
	s_waitcnt lgkmcnt(0)
	v_add_f32_e32 v150, v150, v151
	v_fmamk_f32 v150, v150, 0x3a000000, v158
	v_div_scale_f32 v151, s[4:5], v150, v150, 1.0
	v_rcp_f32_e32 v160, v151
	v_div_scale_f32 v161, vcc, 1.0, v150, 1.0
	s_mov_b64 s[4:5], 0
	v_fma_f32 v162, -v151, v160, 1.0
	v_fmac_f32_e32 v160, v162, v160
	v_mul_f32_e32 v162, v161, v160
	v_fma_f32 v163, -v151, v162, v161
	v_fmac_f32_e32 v162, v163, v160
	v_fma_f32 v151, -v151, v162, v161
	v_div_fmas_f32 v151, v151, v160, v162
	v_div_fixup_f32 v160, v151, v150, 1.0

.LBB0_643:
	s_setprio 0
	s_cmp_gt_i32 s67, 8
	s_cselect_b64 s[2:3], -1, 0
	s_and_b64 s[4:5], s[8:9], s[2:3]
	s_andn2_b64 vcc, exec, s[4:5]
	s_cbranch_vccnz .LBB0_697
	s_waitcnt vmcnt(0)
	s_waitcnt vmcnt(0) lgkmcnt(0)
	s_barrier
	s_and_saveexec_b64 s[4:5], s[96:97]
	s_cbranch_execz .LBB0_696
	s_add_i32 s6, 0, 0x26960
	v_mov_b32_e32 v1, s6
	s_waitcnt vmcnt(0) expcnt(0) lgkmcnt(0)
	ds_read_b32 v3, v1
	s_add_i32 s6, 0, 0x26964
	v_mov_b32_e32 v1, s6
	ds_read_b32 v1, v1
	s_waitcnt lgkmcnt(1)
	v_cmp_ne_u32_e32 vcc, 0, v3
	s_cbranch_vccnz .LBB0_660
	v_readlane_b32 s6, v253, 0
	v_readlane_b32 s7, v253, 1
	s_load_dwordx2 s[10:11], s[6:7], 0x4
	s_add_u32 s6, s50, 0x4200
	s_addc_u32 s7, s51, 0
	s_add_u32 s8, s50, 0x4400
	s_addc_u32 s9, s51, 0
	s_waitcnt lgkmcnt(0)
	s_mul_i32 s33, s10, s92
	s_add_u32 s10, s50, 0x4500
	s_mul_i32 s33, s33, s11
	s_addc_u32 s11, s51, 0
	s_add_u32 s12, s50, 0x4600
	s_addc_u32 s13, s51, 0
	s_add_u32 s14, s50, 0x4700
	s_addc_u32 s15, s51, 0
	s_add_u32 s16, s50, 0x4800
	s_addc_u32 s17, s51, 0
	s_add_u32 s18, s50, 0x4900
	s_addc_u32 s19, s51, 0
	s_add_u32 s20, s50, 0x4a00
	s_addc_u32 s21, s51, 0
	s_add_u32 s22, s50, 0x4b00
	s_addc_u32 s23, s51, 0
	s_add_u32 s26, s50, 0x4c00
	s_addc_u32 s27, s51, 0
	s_add_u32 s28, s50, 0x4d00
	s_addc_u32 s29, s51, 0
	s_add_u32 s30, s50, 0x4e00
	s_addc_u32 s31, s51, 0
	s_add_u32 s34, s50, 0x4f00
	s_addc_u32 s35, s51, 0
	s_add_u32 s36, s50, 0x5000
	s_addc_u32 s37, s51, 0
	s_add_u32 s38, s50, 0x5100
	s_addc_u32 s39, s51, 0
	s_add_u32 s40, s50, 0x5200
	s_addc_u32 s41, s51, 0
	s_add_u32 s42, s50, 0x5300
	s_addc_u32 s43, s51, 0
	s_mov_b32 s50, 1
	v_mov_b32_e32 v17, 0
	s_branch .LBB0_648

.LBB0_697:
	s_cmp_lt_i32 s66, 9
	s_cselect_b64 s[4:5], -1, 0
	s_and_b64 s[2:3], s[4:5], s[2:3]
	s_andn2_b64 vcc, exec, s[2:3]
	s_cbranch_vccnz .LBB0_753
	s_andn2_b64 vcc, exec, s[0:1]
	s_cbranch_vccnz .LBB0_753
	s_lshl_b32 s0, s64, 2
	s_and_b32 s0, s0, 28
	s_ashr_i32 s1, s64, 6
	s_add_i32 s8, s0, s1
	s_cmp_gt_i32 s8, 63
	v_readfirstlane_b32 s0, v0
	s_cbranch_scc1 .LBB0_753
	s_cmpk_lt_u32 s0, 0x100
	s_cbranch_scc0 .Lsp_g4
	s_setprio 1
.Lsp_g4:
	v_lshrrev_b32_e32 v1, 5, v0
	s_waitcnt vmcnt(0) lgkmcnt(0)
	v_lshrrev_b32_e32 v3, 1, v0
	v_and_b32_e32 v1, 4, v1
	v_bfe_u32 v2, v0, 2, 2
	v_and_b32_e32 v3, 24, v3
	v_or3_b32 v2, v1, v2, v3
	v_lshlrev_b32_e32 v3, 4, v0
	v_or_b32_e32 v1, 0x2000, v3
	v_lshrrev_b32_e32 v4, 7, v1
	s_movk_i32 s3, 0x60
	v_and_b32_e32 v6, 32, v0
	s_lshr_b32 s2, s0, 6
	s_bfe_u32 s27, s64, 0x30003
	v_and_or_b32 v5, v4, s3, v2
	v_bitop3_b32 v10, v3, v6, 48 bitop3:0x6c
	v_and_b32_e32 v11, 64, v0
	v_bfe_u32 v12, v0, 2, 4
	s_movk_i32 s3, 0x70
	s_ashr_i32 s9, s8, 31
	s_lshr_b32 s1, s0, 8
	s_lshl_b32 s33, s2, 10
	v_or_b32_e32 v3, v10, v11
	v_and_or_b32 v4, v4, s3, v12
	s_lshl_b64 s[4:5], s[8:9], 22
	s_lshl_b32 s26, s27, 22
	v_lshl_or_b32 v130, v4, 14, v3
	v_lshrrev_b32_e32 v4, 3, v0
	s_add_u32 s10, s24, s26
	v_and_or_b32 v2, v4, 32, v2
	s_addc_u32 s11, s25, 0
	s_add_i32 s9, s33, 0
	v_lshl_or_b32 v132, v2, 14, v3
	s_add_i32 m0, s9, 0x10000
	v_lshl_or_b32 v128, v5, 14, v3
	global_load_lds_dwordx4 v132, s[10:11]
	s_add_i32 m0, s9, 0x12000
	s_add_u32 s6, s10, 0x200000
	global_load_lds_dwordx4 v128, s[10:11]
	s_addc_u32 s7, s11, 0
	s_add_i32 m0, s9, 0x14000
	v_and_or_b32 v2, v4, 48, v12
	global_load_lds_dwordx4 v132, s[6:7]
	s_add_i32 m0, s9, 0x16000
	s_add_u32 s12, s88, s4
	s_addc_u32 s13, s89, s5
	s_add_i32 s38, s9, 0x2000
	v_lshl_or_b32 v134, v2, 14, v3
	global_load_lds_dwordx4 v128, s[6:7]
	s_mov_b32 m0, s9
	s_add_u32 s4, s12, 0x200000
	global_load_lds_dwordx4 v134, s[12:13]
	s_mov_b32 m0, s38
	s_addc_u32 s5, s13, 0
	s_add_i32 s39, s9, 0x4000
	global_load_lds_dwordx4 v130, s[12:13]
	s_mov_b32 m0, s39
	s_add_i32 s40, s9, 0x6000
	global_load_lds_dwordx4 v134, s[4:5]
	s_mov_b32 m0, s40
	v_mov_b32_e32 v133, 0
	global_load_lds_dwordx4 v130, s[4:5]
	v_mov_b32_e32 v129, v133
	v_mov_b32_e32 v135, v133
	v_mov_b32_e32 v131, v133
	s_cmp_eq_u32 s1, 1
	s_mov_b32 s41, 0
	v_lshl_add_u64 v[8:9], s[10:11], 0, v[132:133]
	v_lshl_add_u64 v[6:7], s[10:11], 0, v[128:129]
	v_lshl_add_u64 v[2:3], s[12:13], 0, v[134:135]
	s_cselect_b64 s[14:15], -1, 0
	s_cmp_lg_u32 s1, 1
	v_lshl_add_u64 v[4:5], s[12:13], 0, v[130:131]
	s_cbranch_scc1 .LBB0_702
	s_barrier

.LBB0_706:
	ds_read_b128 v[152:155], v181
	ds_read_b128 v[156:159], v181 offset:1024
	ds_read_b128 v[188:191], v181 offset:2048
	ds_read_b128 v[192:195], v181 offset:3072
	ds_read_b128 v[196:199], v182
	ds_read_b128 v[200:203], v182 offset:1024
	ds_read_b128 v[204:207], v182 offset:2048
	ds_read_b128 v[208:211], v182 offset:3072
	s_add_u32 s34, s28, s30
	s_addc_u32 s35, s29, s31
	s_add_u32 s34, s34, 0x100
	s_addc_u32 s35, s35, 0
	s_add_u32 s66, s56, s30
	s_addc_u32 s67, s57, s31
	s_cmpk_eq_i32 s30, 0x3f00
	s_cselect_b32 s37, s63, s35
	s_cselect_b32 s36, s64, s34
	s_cselect_b32 s35, s11, s67
	s_cselect_b32 s34, s10, s66
	v_lshl_add_u64 v[160:161], v[148:149], 0, s[30:31]
	s_add_i32 m0, s9, 0xc000
	ds_read_b128 v[212:215], v183
	ds_read_b128 v[216:219], v183 offset:1024
	ds_read_b128 v[220:223], v183 offset:2048
	ds_read_b128 v[224:227], v183 offset:3072
	ds_read_b128 v[228:231], v183 offset:4096
	ds_read_b128 v[232:235], v183 offset:5120
	ds_read_b128 v[236:239], v183 offset:6144
	ds_read_b128 v[240:243], v183 offset:7168
	global_load_lds_dwordx4 v[160:161], off
	v_lshl_add_u64 v[160:161], v[150:151], 0, s[30:31]
	s_add_i32 m0, s9, 0xe000
	s_nop 0
	global_load_lds_dwordx4 v[160:161], off
	s_waitcnt vmcnt(8)
	s_waitcnt lgkmcnt(0)
	s_barrier
	s_waitcnt lgkmcnt(0)
	v_mfma_f32_16x16x32_bf16 v[124:127], v[152:155], v[212:215], v[124:127]
	v_mfma_f32_16x16x32_bf16 v[120:123], v[188:191], v[212:215], v[120:123]
	v_mfma_f32_16x16x32_bf16 v[108:111], v[152:155], v[220:223], v[108:111]
	v_mfma_f32_16x16x32_bf16 v[104:107], v[188:191], v[220:223], v[104:107]
	v_mfma_f32_16x16x32_bf16 v[92:95], v[152:155], v[228:231], v[92:95]
	v_mfma_f32_16x16x32_bf16 v[88:91], v[188:191], v[228:231], v[88:91]
	v_mfma_f32_16x16x32_bf16 v[76:79], v[152:155], v[236:239], v[76:79]
	v_mfma_f32_16x16x32_bf16 v[72:75], v[188:191], v[236:239], v[72:75]
	v_mfma_f32_16x16x32_bf16 v[124:127], v[156:159], v[216:219], v[124:127]
	v_mfma_f32_16x16x32_bf16 v[120:123], v[192:195], v[216:219], v[120:123]
	v_mfma_f32_16x16x32_bf16 v[108:111], v[156:159], v[224:227], v[108:111]
	v_mfma_f32_16x16x32_bf16 v[104:107], v[192:195], v[224:227], v[104:107]
	v_mfma_f32_16x16x32_bf16 v[92:95], v[156:159], v[232:235], v[92:95]
	v_mfma_f32_16x16x32_bf16 v[88:91], v[192:195], v[232:235], v[88:91]
	v_mfma_f32_16x16x32_bf16 v[76:79], v[156:159], v[240:243], v[76:79]
	v_mfma_f32_16x16x32_bf16 v[72:75], v[192:195], v[240:243], v[72:75]
	v_mfma_f32_16x16x32_bf16 v[116:119], v[196:199], v[212:215], v[116:119]
	v_mfma_f32_16x16x32_bf16 v[112:115], v[204:207], v[212:215], v[112:115]
	v_mfma_f32_16x16x32_bf16 v[100:103], v[196:199], v[220:223], v[100:103]
	v_mfma_f32_16x16x32_bf16 v[96:99], v[204:207], v[220:223], v[96:99]
	v_mfma_f32_16x16x32_bf16 v[84:87], v[196:199], v[228:231], v[84:87]
	v_mfma_f32_16x16x32_bf16 v[80:83], v[204:207], v[228:231], v[80:83]
	v_mfma_f32_16x16x32_bf16 v[68:71], v[196:199], v[236:239], v[68:71]
	v_mfma_f32_16x16x32_bf16 v[64:67], v[204:207], v[236:239], v[64:67]
	v_mfma_f32_16x16x32_bf16 v[116:119], v[200:203], v[216:219], v[116:119]
	v_mfma_f32_16x16x32_bf16 v[112:115], v[208:211], v[216:219], v[112:115]
	v_mfma_f32_16x16x32_bf16 v[100:103], v[200:203], v[224:227], v[100:103]
	v_mfma_f32_16x16x32_bf16 v[96:99], v[208:211], v[224:227], v[96:99]
	v_mfma_f32_16x16x32_bf16 v[84:87], v[200:203], v[232:235], v[84:87]
	v_mfma_f32_16x16x32_bf16 v[80:83], v[208:211], v[232:235], v[80:83]
	v_mfma_f32_16x16x32_bf16 v[68:71], v[200:203], v[240:243], v[68:71]
	v_mfma_f32_16x16x32_bf16 v[64:67], v[208:211], v[240:243], v[64:67]
	s_barrier
	s_add_i32 s66, s58, s33
	v_lshl_add_u64 v[160:161], s[34:35], 0, v[132:133]
	s_mov_b32 m0, s66
	ds_read_b128 v[212:215], v183 offset:16384
	ds_read_b128 v[216:219], v183 offset:17408
	ds_read_b128 v[220:223], v183 offset:18432
	ds_read_b128 v[224:227], v183 offset:19456
	ds_read_b128 v[228:231], v183 offset:20480
	ds_read_b128 v[232:235], v183 offset:21504
	ds_read_b128 v[236:239], v183 offset:22528
	ds_read_b128 v[240:243], v183 offset:23552
	global_load_lds_dwordx4 v[160:161], off
	s_add_i32 m0, s66, 0x2000
	s_add_u32 s66, s34, 0x200000
	v_lshl_add_u64 v[244:245], s[34:35], 0, v[128:129]
	s_addc_u32 s67, s35, 0
	s_add_i32 s68, s59, s33
	global_load_lds_dwordx4 v[244:245], off
	v_lshl_add_u64 v[246:247], s[66:67], 0, v[132:133]
	s_mov_b32 m0, s68
	v_lshl_add_u64 v[248:249], s[36:37], 0, v[130:131]
	global_load_lds_dwordx4 v[246:247], off
	v_lshl_add_u64 v[246:247], s[66:67], 0, v[128:129]
	s_add_i32 m0, s68, 0x2000
	s_nop 0
	global_load_lds_dwordx4 v[246:247], off
	v_lshl_add_u64 v[246:247], s[36:37], 0, v[134:135]
	s_mov_b32 m0, s9
	s_nop 0
	global_load_lds_dwordx4 v[246:247], off
	s_mov_b32 m0, s38
	s_nop 0
	global_load_lds_dwordx4 v[248:249], off
	s_waitcnt vmcnt(8)
	s_waitcnt lgkmcnt(0)
	s_barrier
	s_waitcnt lgkmcnt(0)
	v_mfma_f32_16x16x32_bf16 v[60:63], v[152:155], v[212:215], v[60:63]
	v_mfma_f32_16x16x32_bf16 v[56:59], v[188:191], v[212:215], v[56:59]
	v_mfma_f32_16x16x32_bf16 v[44:47], v[152:155], v[220:223], v[44:47]
	v_mfma_f32_16x16x32_bf16 v[40:43], v[188:191], v[220:223], v[40:43]
	v_mfma_f32_16x16x32_bf16 v[28:31], v[152:155], v[228:231], v[28:31]
	v_mfma_f32_16x16x32_bf16 v[24:27], v[188:191], v[228:231], v[24:27]
	v_mfma_f32_16x16x32_bf16 v[12:15], v[152:155], v[236:239], v[12:15]
	v_mfma_f32_16x16x32_bf16 v[8:11], v[188:191], v[236:239], v[8:11]
	v_mfma_f32_16x16x32_bf16 v[60:63], v[156:159], v[216:219], v[60:63]
	v_mfma_f32_16x16x32_bf16 v[56:59], v[192:195], v[216:219], v[56:59]
	v_mfma_f32_16x16x32_bf16 v[44:47], v[156:159], v[224:227], v[44:47]
	v_mfma_f32_16x16x32_bf16 v[40:43], v[192:195], v[224:227], v[40:43]
	v_mfma_f32_16x16x32_bf16 v[28:31], v[156:159], v[232:235], v[28:31]
	v_mfma_f32_16x16x32_bf16 v[24:27], v[192:195], v[232:235], v[24:27]
	v_mfma_f32_16x16x32_bf16 v[12:15], v[156:159], v[240:243], v[12:15]
	v_mfma_f32_16x16x32_bf16 v[8:11], v[192:195], v[240:243], v[8:11]
	v_mfma_f32_16x16x32_bf16 v[52:55], v[196:199], v[212:215], v[52:55]
	v_mfma_f32_16x16x32_bf16 v[48:51], v[204:207], v[212:215], v[48:51]
	v_mfma_f32_16x16x32_bf16 v[36:39], v[196:199], v[220:223], v[36:39]
	v_mfma_f32_16x16x32_bf16 v[32:35], v[204:207], v[220:223], v[32:35]
	v_mfma_f32_16x16x32_bf16 v[20:23], v[196:199], v[228:231], v[20:23]
	v_mfma_f32_16x16x32_bf16 v[16:19], v[204:207], v[228:231], v[16:19]
	v_mfma_f32_16x16x32_bf16 v[4:7], v[196:199], v[236:239], v[4:7]
	v_mfma_f32_16x16x32_bf16 v[0:3], v[204:207], v[236:239], v[0:3]
	v_mfma_f32_16x16x32_bf16 v[52:55], v[200:203], v[216:219], v[52:55]
	v_mfma_f32_16x16x32_bf16 v[48:51], v[208:211], v[216:219], v[48:51]
	v_mfma_f32_16x16x32_bf16 v[36:39], v[200:203], v[224:227], v[36:39]
	v_mfma_f32_16x16x32_bf16 v[32:35], v[208:211], v[224:227], v[32:35]
	v_mfma_f32_16x16x32_bf16 v[20:23], v[200:203], v[232:235], v[20:23]
	v_mfma_f32_16x16x32_bf16 v[16:19], v[208:211], v[232:235], v[16:19]
	v_mfma_f32_16x16x32_bf16 v[4:7], v[200:203], v[240:243], v[4:7]
	v_mfma_f32_16x16x32_bf16 v[0:3], v[208:211], v[240:243], v[0:3]
	s_barrier
	s_add_i32 s66, 0, 0x18000
	s_add_i32 s67, 0, 0x1c000
	v_add_u32_e32 v192, s66, v164
	v_add_u32_e32 v208, s67, v164
	ds_read_b128 v[152:155], v192
	ds_read_b128 v[156:159], v192 offset:1024
	ds_read_b128 v[188:191], v192 offset:2048
	ds_read_b128 v[192:195], v192 offset:3072
	ds_read_b128 v[196:199], v208
	ds_read_b128 v[200:203], v208 offset:1024
	ds_read_b128 v[204:207], v208 offset:2048
	ds_read_b128 v[208:211], v208 offset:3072
	s_add_u32 s36, s36, 0x200000
	s_addc_u32 s37, s37, 0
	s_mov_b32 m0, s39
	v_lshl_add_u64 v[250:251], s[36:37], 0, v[134:135]
	ds_read_b128 v[212:215], v183 offset:32768
	ds_read_b128 v[216:219], v183 offset:33792
	ds_read_b128 v[220:223], v183 offset:34816
	ds_read_b128 v[224:227], v183 offset:35840
	ds_read_b128 v[228:231], v183 offset:36864
	ds_read_b128 v[232:235], v183 offset:37888
	ds_read_b128 v[236:239], v183 offset:38912
	ds_read_b128 v[240:243], v183 offset:39936
	global_load_lds_dwordx4 v[250:251], off
	v_lshl_add_u64 v[250:251], s[36:37], 0, v[130:131]
	s_mov_b32 m0, s40
	s_nop 0
	global_load_lds_dwordx4 v[250:251], off
	s_waitcnt vmcnt(8)
	s_waitcnt lgkmcnt(0)
	s_barrier
	s_waitcnt lgkmcnt(0)
	v_mfma_f32_16x16x32_bf16 v[124:127], v[152:155], v[212:215], v[124:127]
	v_mfma_f32_16x16x32_bf16 v[120:123], v[188:191], v[212:215], v[120:123]
	v_mfma_f32_16x16x32_bf16 v[108:111], v[152:155], v[220:223], v[108:111]
	v_mfma_f32_16x16x32_bf16 v[104:107], v[188:191], v[220:223], v[104:107]
	v_mfma_f32_16x16x32_bf16 v[92:95], v[152:155], v[228:231], v[92:95]
	v_mfma_f32_16x16x32_bf16 v[88:91], v[188:191], v[228:231], v[88:91]
	v_mfma_f32_16x16x32_bf16 v[76:79], v[152:155], v[236:239], v[76:79]
	v_mfma_f32_16x16x32_bf16 v[72:75], v[188:191], v[236:239], v[72:75]
	v_mfma_f32_16x16x32_bf16 v[124:127], v[156:159], v[216:219], v[124:127]
	v_mfma_f32_16x16x32_bf16 v[120:123], v[192:195], v[216:219], v[120:123]
	v_mfma_f32_16x16x32_bf16 v[108:111], v[156:159], v[224:227], v[108:111]
	v_mfma_f32_16x16x32_bf16 v[104:107], v[192:195], v[224:227], v[104:107]
	v_mfma_f32_16x16x32_bf16 v[92:95], v[156:159], v[232:235], v[92:95]
	v_mfma_f32_16x16x32_bf16 v[88:91], v[192:195], v[232:235], v[88:91]
	v_mfma_f32_16x16x32_bf16 v[76:79], v[156:159], v[240:243], v[76:79]
	v_mfma_f32_16x16x32_bf16 v[72:75], v[192:195], v[240:243], v[72:75]
	v_mfma_f32_16x16x32_bf16 v[116:119], v[196:199], v[212:215], v[116:119]
	v_mfma_f32_16x16x32_bf16 v[112:115], v[204:207], v[212:215], v[112:115]
	v_mfma_f32_16x16x32_bf16 v[100:103], v[196:199], v[220:223], v[100:103]
	v_mfma_f32_16x16x32_bf16 v[96:99], v[204:207], v[220:223], v[96:99]
	v_mfma_f32_16x16x32_bf16 v[84:87], v[196:199], v[228:231], v[84:87]
	v_mfma_f32_16x16x32_bf16 v[80:83], v[204:207], v[228:231], v[80:83]
	v_mfma_f32_16x16x32_bf16 v[68:71], v[196:199], v[236:239], v[68:71]
	v_mfma_f32_16x16x32_bf16 v[64:67], v[204:207], v[236:239], v[64:67]
	v_mfma_f32_16x16x32_bf16 v[116:119], v[200:203], v[216:219], v[116:119]
	v_mfma_f32_16x16x32_bf16 v[112:115], v[208:211], v[216:219], v[112:115]
	v_mfma_f32_16x16x32_bf16 v[100:103], v[200:203], v[224:227], v[100:103]
	v_mfma_f32_16x16x32_bf16 v[96:99], v[208:211], v[224:227], v[96:99]
	v_mfma_f32_16x16x32_bf16 v[84:87], v[200:203], v[232:235], v[84:87]
	v_mfma_f32_16x16x32_bf16 v[80:83], v[208:211], v[232:235], v[80:83]
	v_mfma_f32_16x16x32_bf16 v[68:71], v[200:203], v[240:243], v[68:71]
	v_mfma_f32_16x16x32_bf16 v[64:67], v[208:211], v[240:243], v[64:67]
	s_barrier
	s_add_i32 s36, s66, s33
	v_lshl_add_u64 v[160:161], v[160:161], 0, s[18:19]
	s_mov_b32 m0, s36
	ds_read_b128 v[212:215], v183 offset:49152
	ds_read_b128 v[216:219], v183 offset:50176
	ds_read_b128 v[220:223], v183 offset:51200
	ds_read_b128 v[224:227], v183 offset:52224
	ds_read_b128 v[228:231], v183 offset:53248
	ds_read_b128 v[232:235], v183 offset:54272
	ds_read_b128 v[236:239], v183 offset:55296
	ds_read_b128 v[240:243], v183 offset:56320
	global_load_lds_dwordx4 v[160:161], off
	s_add_i32 m0, s36, 0x2000
	s_add_u32 s34, s34, 0x200080
	v_lshl_add_u64 v[160:161], v[244:245], 0, s[18:19]
	s_addc_u32 s35, s35, 0
	s_add_i32 s36, s67, s33
	global_load_lds_dwordx4 v[160:161], off
	v_lshl_add_u64 v[160:161], s[34:35], 0, v[132:133]
	s_mov_b32 m0, s36
	s_nop 0
	global_load_lds_dwordx4 v[160:161], off
	v_lshl_add_u64 v[160:161], s[34:35], 0, v[128:129]
	s_add_i32 m0, s36, 0x2000
	s_nop 0
	global_load_lds_dwordx4 v[160:161], off
	v_lshl_add_u64 v[160:161], v[246:247], 0, s[18:19]
	s_mov_b32 m0, s45
	s_nop 0
	global_load_lds_dwordx4 v[160:161], off
	v_lshl_add_u64 v[160:161], v[248:249], 0, s[18:19]
	s_mov_b32 m0, s46
	s_nop 0
	global_load_lds_dwordx4 v[160:161], off
	s_waitcnt vmcnt(8)
	s_waitcnt lgkmcnt(0)
	s_barrier
	s_waitcnt lgkmcnt(0)
	v_mfma_f32_16x16x32_bf16 v[60:63], v[152:155], v[212:215], v[60:63]
	v_mfma_f32_16x16x32_bf16 v[56:59], v[188:191], v[212:215], v[56:59]
	v_mfma_f32_16x16x32_bf16 v[44:47], v[152:155], v[220:223], v[44:47]
	v_mfma_f32_16x16x32_bf16 v[40:43], v[188:191], v[220:223], v[40:43]
	v_mfma_f32_16x16x32_bf16 v[28:31], v[152:155], v[228:231], v[28:31]
	v_mfma_f32_16x16x32_bf16 v[24:27], v[188:191], v[228:231], v[24:27]
	v_mfma_f32_16x16x32_bf16 v[12:15], v[152:155], v[236:239], v[12:15]
	v_mfma_f32_16x16x32_bf16 v[8:11], v[188:191], v[236:239], v[8:11]
	v_mfma_f32_16x16x32_bf16 v[60:63], v[156:159], v[216:219], v[60:63]
	v_mfma_f32_16x16x32_bf16 v[56:59], v[192:195], v[216:219], v[56:59]
	v_mfma_f32_16x16x32_bf16 v[44:47], v[156:159], v[224:227], v[44:47]
	v_mfma_f32_16x16x32_bf16 v[40:43], v[192:195], v[224:227], v[40:43]
	v_mfma_f32_16x16x32_bf16 v[28:31], v[156:159], v[232:235], v[28:31]
	v_mfma_f32_16x16x32_bf16 v[24:27], v[192:195], v[232:235], v[24:27]
	v_mfma_f32_16x16x32_bf16 v[12:15], v[156:159], v[240:243], v[12:15]
	v_mfma_f32_16x16x32_bf16 v[8:11], v[192:195], v[240:243], v[8:11]
	v_mfma_f32_16x16x32_bf16 v[52:55], v[196:199], v[212:215], v[52:55]
	v_mfma_f32_16x16x32_bf16 v[48:51], v[204:207], v[212:215], v[48:51]
	v_mfma_f32_16x16x32_bf16 v[36:39], v[196:199], v[220:223], v[36:39]
	v_mfma_f32_16x16x32_bf16 v[32:35], v[204:207], v[220:223], v[32:35]
	v_mfma_f32_16x16x32_bf16 v[20:23], v[196:199], v[228:231], v[20:23]
	v_mfma_f32_16x16x32_bf16 v[16:19], v[204:207], v[228:231], v[16:19]
	v_mfma_f32_16x16x32_bf16 v[4:7], v[196:199], v[236:239], v[4:7]
	v_mfma_f32_16x16x32_bf16 v[0:3], v[204:207], v[236:239], v[0:3]
	v_mfma_f32_16x16x32_bf16 v[52:55], v[200:203], v[216:219], v[52:55]
	v_mfma_f32_16x16x32_bf16 v[48:51], v[208:211], v[216:219], v[48:51]
	v_mfma_f32_16x16x32_bf16 v[36:39], v[200:203], v[224:227], v[36:39]
	v_mfma_f32_16x16x32_bf16 v[32:35], v[208:211], v[224:227], v[32:35]
	v_mfma_f32_16x16x32_bf16 v[20:23], v[200:203], v[232:235], v[20:23]
	v_mfma_f32_16x16x32_bf16 v[16:19], v[208:211], v[232:235], v[16:19]
	v_mfma_f32_16x16x32_bf16 v[4:7], v[200:203], v[240:243], v[4:7]
	v_mfma_f32_16x16x32_bf16 v[0:3], v[208:211], v[240:243], v[0:3]
	s_barrier
	s_add_i32 s65, s65, 2
	s_add_u32 s30, s30, 0x100
	s_addc_u32 s31, s31, 0
	s_cmpk_gt_u32 s65, 0x7d
	s_cbranch_scc0 .LBB0_706
	s_and_b64 vcc, exec, s[20:21]
	s_cbranch_vccz .LBB0_709
	s_barrier

.LBB0_753:
	s_setprio 0
	s_endpgm
